# v17 + non-temporal hint on the read-once f32 weight / input loads of the prologue conversion
# speedup vs baseline: 1.0059x; 1.0059x over previous
; __device__ __forceinline__ void conv_weight(const float* W, int ldw, int K, int Nphys, int Nvalid, int mode, const float* g, bf16_t* WT, LAS float* scr, int gw, int NGW, int lane, int& rot) {
;     ...
;     for (int it = g0; it < items; it += NGW) {
;         const int kb = it / nblk, nb = it % nblk, k0 = 64 * kb, n0 = 32 * nb;
;         const int prow = n0 + (lane & 31); const bool ok = prow < Nvalid; const int col = ok ? colmap(mode, prow) : 0;
;         float wv_[32];
; #pragma unroll
;         for (int i = 0; i < 32; ++i) { const int kk = 2 * i + (lane >> 5); wv_[i] = ok ? W[(size_t)(k0 + kk) * ldw + col] : 0.f; }
.LBB0_16:
	s_or_b64 exec, exec, s[18:19]
	s_lshl_b32 s18, s35, 6
	v_lshl_add_u64 v[28:29], v[10:11], 2, s[12:13]
	v_or_b32_e32 v26, s18, v2
	v_mov_b32_e32 v41, 0
	v_mov_b32_e32 v40, 0
	s_and_saveexec_b64 s[20:21], s[4:5]
	s_cbranch_execz .LBB0_18
	v_mad_i64_i32 v[8:9], s[22:23], v26, s30, v[28:29]
	global_load_dword v40, v[8:9], off nt
.LBB0_18:
	s_or_b64 exec, exec, s[20:21]
	s_and_saveexec_b64 s[20:21], s[4:5]
	s_cbranch_execz .LBB0_20
	v_or_b32_e32 v8, 2, v26
	v_mad_i64_i32 v[8:9], s[22:23], v8, s30, v[28:29]
	global_load_dword v41, v[8:9], off nt
.LBB0_20:
	s_or_b64 exec, exec, s[20:21]
	v_mov_b32_e32 v9, 0
	v_mov_b32_e32 v8, 0
	s_and_saveexec_b64 s[20:21], s[4:5]
	s_cbranch_execz .LBB0_22
	v_or_b32_e32 v8, 4, v26
	v_mad_i64_i32 v[10:11], s[22:23], v8, s30, v[28:29]
	global_load_dword v8, v[10:11], off nt
.LBB0_22:
	s_or_b64 exec, exec, s[20:21]
	s_and_saveexec_b64 s[20:21], s[4:5]
	s_cbranch_execz .LBB0_24
	v_or_b32_e32 v9, 6, v26
	v_mad_i64_i32 v[10:11], s[22:23], v9, s30, v[28:29]
	global_load_dword v9, v[10:11], off nt
.LBB0_24:
	s_or_b64 exec, exec, s[20:21]
	v_mov_b32_e32 v42, 0
	v_mov_b32_e32 v43, 0
	s_and_saveexec_b64 s[20:21], s[4:5]
	s_cbranch_execz .LBB0_26
	v_or_b32_e32 v10, 8, v26
	v_mad_i64_i32 v[10:11], s[22:23], v10, s30, v[28:29]
	global_load_dword v43, v[10:11], off nt
.LBB0_26:
	s_or_b64 exec, exec, s[20:21]
	s_and_saveexec_b64 s[20:21], s[4:5]
	s_cbranch_execz .LBB0_28
	v_or_b32_e32 v10, 10, v26
	v_mad_i64_i32 v[10:11], s[22:23], v10, s30, v[28:29]
	global_load_dword v42, v[10:11], off nt
.LBB0_28:
	s_or_b64 exec, exec, s[20:21]
	v_mov_b32_e32 v11, 0
	v_mov_b32_e32 v10, 0
	s_and_saveexec_b64 s[20:21], s[4:5]
	s_cbranch_execz .LBB0_30
	v_or_b32_e32 v10, 12, v26
	v_mad_i64_i32 v[12:13], s[22:23], v10, s30, v[28:29]
	global_load_dword v10, v[12:13], off nt
.LBB0_30:
	s_or_b64 exec, exec, s[20:21]
	s_and_saveexec_b64 s[20:21], s[4:5]
	s_cbranch_execz .LBB0_32
	v_or_b32_e32 v11, 14, v26
	v_mad_i64_i32 v[12:13], s[22:23], v11, s30, v[28:29]
	global_load_dword v11, v[12:13], off nt
.LBB0_32:
	s_or_b64 exec, exec, s[20:21]
	v_mov_b32_e32 v44, 0
	v_mov_b32_e32 v45, 0
	s_and_saveexec_b64 s[20:21], s[4:5]
	s_cbranch_execz .LBB0_34
	v_or_b32_e32 v12, 16, v26
	v_mad_i64_i32 v[12:13], s[22:23], v12, s30, v[28:29]
	global_load_dword v45, v[12:13], off nt
.LBB0_34:
	s_or_b64 exec, exec, s[20:21]
	s_and_saveexec_b64 s[20:21], s[4:5]
	s_cbranch_execz .LBB0_36
	v_or_b32_e32 v12, 18, v26
	v_mad_i64_i32 v[12:13], s[22:23], v12, s30, v[28:29]
	global_load_dword v44, v[12:13], off nt
.LBB0_36:
	s_or_b64 exec, exec, s[20:21]
	v_mov_b32_e32 v15, 0
	v_mov_b32_e32 v14, 0
	s_and_saveexec_b64 s[20:21], s[4:5]
	s_cbranch_execz .LBB0_38
	v_or_b32_e32 v12, 20, v26
	v_mad_i64_i32 v[12:13], s[22:23], v12, s30, v[28:29]
	global_load_dword v14, v[12:13], off nt
.LBB0_38:
	s_or_b64 exec, exec, s[20:21]
	s_and_saveexec_b64 s[20:21], s[4:5]
	s_cbranch_execz .LBB0_40
	v_or_b32_e32 v12, 22, v26
	v_mad_i64_i32 v[12:13], s[22:23], v12, s30, v[28:29]
	global_load_dword v15, v[12:13], off nt
.LBB0_40:
	s_or_b64 exec, exec, s[20:21]
	v_mov_b32_e32 v46, 0
	v_mov_b32_e32 v47, 0
	s_and_saveexec_b64 s[20:21], s[4:5]
	s_cbranch_execz .LBB0_42
	v_or_b32_e32 v12, 24, v26
	v_mad_i64_i32 v[12:13], s[22:23], v12, s30, v[28:29]
	global_load_dword v47, v[12:13], off nt
.LBB0_42:
	s_or_b64 exec, exec, s[20:21]
	s_and_saveexec_b64 s[20:21], s[4:5]
	s_cbranch_execz .LBB0_44
	v_or_b32_e32 v12, 26, v26
	v_mad_i64_i32 v[12:13], s[22:23], v12, s30, v[28:29]
	global_load_dword v46, v[12:13], off nt
.LBB0_44:
	s_or_b64 exec, exec, s[20:21]
	v_mov_b32_e32 v17, 0
	v_mov_b32_e32 v16, 0
	s_and_saveexec_b64 s[20:21], s[4:5]
	s_cbranch_execz .LBB0_46
	v_or_b32_e32 v12, 28, v26
	v_mad_i64_i32 v[12:13], s[22:23], v12, s30, v[28:29]
	global_load_dword v16, v[12:13], off nt
.LBB0_46:
	s_or_b64 exec, exec, s[20:21]
	s_and_saveexec_b64 s[20:21], s[4:5]
	s_cbranch_execz .LBB0_48
	v_or_b32_e32 v12, 30, v26
	v_mad_i64_i32 v[12:13], s[22:23], v12, s30, v[28:29]
	global_load_dword v17, v[12:13], off nt
.LBB0_48:
	s_or_b64 exec, exec, s[20:21]
	v_mov_b32_e32 v48, 0
	v_mov_b32_e32 v49, 0
	s_and_saveexec_b64 s[20:21], s[4:5]
	s_cbranch_execz .LBB0_50
	v_or_b32_e32 v12, 32, v26
	v_mad_i64_i32 v[12:13], s[22:23], v12, s30, v[28:29]
	global_load_dword v49, v[12:13], off nt
; __device__ __forceinline__ void conv_weight(const float* W, int ldw, int K, int Nphys, int Nvalid, int mode, const float* g, bf16_t* WT, LAS float* scr, int gw, int NGW, int lane, int& rot) {
;     ...
;         for (int i = 0; i < 32; ++i) { const int kk = 2 * i + (lane >> 5); wv_[i] = ok ? W[(size_t)(k0 + kk) * ldw + col] : 0.f; }
; #pragma unroll
;         for (int i = 0; i < 32; ++i) { const int kk = 2 * i + (lane >> 5); float v = wv_[i]; if (g) v *= g[k0 + kk]; scr[kk * 33 + (lane & 31)] = v; }
.LBB0_50:
	s_or_b64 exec, exec, s[20:21]
	s_and_saveexec_b64 s[20:21], s[4:5]
	s_cbranch_execz .LBB0_52
	v_or_b32_e32 v12, 34, v26
	v_mad_i64_i32 v[12:13], s[22:23], v12, s30, v[28:29]
	global_load_dword v48, v[12:13], off nt
.LBB0_52:
	s_or_b64 exec, exec, s[20:21]
	v_mov_b32_e32 v21, 0
	v_mov_b32_e32 v20, 0
	s_and_saveexec_b64 s[20:21], s[4:5]
	s_cbranch_execz .LBB0_54
	v_or_b32_e32 v12, 36, v26
	v_mad_i64_i32 v[12:13], s[22:23], v12, s30, v[28:29]
	global_load_dword v20, v[12:13], off nt
.LBB0_54:
	s_or_b64 exec, exec, s[20:21]
	s_and_saveexec_b64 s[20:21], s[4:5]
	s_cbranch_execz .LBB0_56
	v_or_b32_e32 v12, 38, v26
	v_mad_i64_i32 v[12:13], s[22:23], v12, s30, v[28:29]
	global_load_dword v21, v[12:13], off nt
.LBB0_56:
	s_or_b64 exec, exec, s[20:21]
	v_mov_b32_e32 v51, 0
	v_mov_b32_e32 v53, 0
	s_and_saveexec_b64 s[20:21], s[4:5]
	s_cbranch_execz .LBB0_58
	v_or_b32_e32 v12, 40, v26
	v_mad_i64_i32 v[12:13], s[22:23], v12, s30, v[28:29]
	global_load_dword v53, v[12:13], off nt
.LBB0_58:
	s_or_b64 exec, exec, s[20:21]
	s_and_saveexec_b64 s[20:21], s[4:5]
	s_cbranch_execz .LBB0_60
	v_or_b32_e32 v12, 42, v26
	v_mad_i64_i32 v[12:13], s[22:23], v12, s30, v[28:29]
	global_load_dword v51, v[12:13], off nt
.LBB0_60:
	s_or_b64 exec, exec, s[20:21]
	v_mov_b32_e32 v23, 0
	v_mov_b32_e32 v22, 0
	s_and_saveexec_b64 s[20:21], s[4:5]
	s_cbranch_execz .LBB0_62
	v_or_b32_e32 v12, 44, v26
	v_mad_i64_i32 v[12:13], s[22:23], v12, s30, v[28:29]
	global_load_dword v22, v[12:13], off nt
.LBB0_62:
	s_or_b64 exec, exec, s[20:21]
	s_and_saveexec_b64 s[20:21], s[4:5]
	s_cbranch_execz .LBB0_64
	v_or_b32_e32 v12, 46, v26
	v_mad_i64_i32 v[12:13], s[22:23], v12, s30, v[28:29]
	global_load_dword v23, v[12:13], off nt
.LBB0_64:
	s_or_b64 exec, exec, s[20:21]
	v_mov_b32_e32 v54, 0
	v_mov_b32_e32 v55, 0
	s_and_saveexec_b64 s[20:21], s[4:5]
	s_cbranch_execz .LBB0_66
	v_or_b32_e32 v12, 48, v26
	v_mad_i64_i32 v[12:13], s[22:23], v12, s30, v[28:29]
	global_load_dword v55, v[12:13], off nt
.LBB0_66:
	s_or_b64 exec, exec, s[20:21]
	s_and_saveexec_b64 s[20:21], s[4:5]
	s_cbranch_execz .LBB0_68
	v_or_b32_e32 v12, 50, v26
	v_mad_i64_i32 v[12:13], s[22:23], v12, s30, v[28:29]
	global_load_dword v54, v[12:13], off nt
.LBB0_68:
	s_or_b64 exec, exec, s[20:21]
	v_mov_b32_e32 v25, 0
	v_mov_b32_e32 v24, 0
	s_and_saveexec_b64 s[20:21], s[4:5]
	s_cbranch_execz .LBB0_70
	v_or_b32_e32 v12, 52, v26
	v_mad_i64_i32 v[12:13], s[22:23], v12, s30, v[28:29]
	global_load_dword v24, v[12:13], off nt
.LBB0_70:
	s_or_b64 exec, exec, s[20:21]
	s_and_saveexec_b64 s[20:21], s[4:5]
	s_cbranch_execz .LBB0_72
	v_or_b32_e32 v12, 54, v26
	v_mad_i64_i32 v[12:13], s[22:23], v12, s30, v[28:29]
	global_load_dword v25, v[12:13], off nt
.LBB0_72:
	s_or_b64 exec, exec, s[20:21]
	v_mov_b32_e32 v50, 0
	v_mov_b32_e32 v52, 0
	s_and_saveexec_b64 s[20:21], s[4:5]
	s_cbranch_execz .LBB0_74
	v_or_b32_e32 v12, 56, v26
	v_mad_i64_i32 v[12:13], s[22:23], v12, s30, v[28:29]
	global_load_dword v52, v[12:13], off nt
.LBB0_74:
	s_or_b64 exec, exec, s[20:21]
	s_and_saveexec_b64 s[20:21], s[4:5]
	s_cbranch_execz .LBB0_76
	v_or_b32_e32 v12, 58, v26
	v_mad_i64_i32 v[12:13], s[22:23], v12, s30, v[28:29]
	global_load_dword v50, v[12:13], off nt
.LBB0_76:
	s_or_b64 exec, exec, s[20:21]
	v_mov_b32_e32 v13, 0
	v_mov_b32_e32 v12, 0
	s_and_saveexec_b64 s[20:21], s[4:5]
	s_cbranch_execz .LBB0_78
	v_or_b32_e32 v12, 60, v26
	v_mad_i64_i32 v[56:57], s[22:23], v12, s30, v[28:29]
	global_load_dword v12, v[56:57], off nt
.LBB0_78:
	s_or_b64 exec, exec, s[20:21]
	s_and_saveexec_b64 s[20:21], s[4:5]
	s_cbranch_execz .LBB0_80
	v_or_b32_e32 v13, 62, v26
	v_mad_i64_i32 v[28:29], s[4:5], v13, s30, v[28:29]
	global_load_dword v13, v[28:29], off nt
.LBB0_80:
	s_or_b64 exec, exec, s[20:21]
	v_cndmask_b32_e64 v27, 0, 1, s[16:17]
	v_cmp_ne_u32_e64 s[4:5], 1, v27
	s_andn2_b64 vcc, exec, s[16:17]
	s_cbranch_vccnz .LBB0_103
	v_ashrrev_i32_e32 v27, 31, v26
	s_ashr_i32 s19, s18, 31
	v_lshl_add_u64 v[26:27], v[26:27], 2, s[14:15]
	v_lshl_add_u64 v[28:29], s[18:19], 0, v[2:3]
	v_lshl_add_u64 v[28:29], v[28:29], 2, s[14:15]
	global_load_dword v58, v[26:27], off nt
	global_load_dword v59, v[28:29], off offset:8
	global_load_dword v56, v[28:29], off offset:16
	global_load_dword v57, v[28:29], off offset:24
	s_waitcnt vmcnt(3)
	v_mul_f32_e32 v28, v40, v58
	s_waitcnt vmcnt(2)
	v_mul_f32_e32 v29, v41, v59
	ds_write2_b32 v37, v28, v29 offset1:66
	s_waitcnt vmcnt(0)
	v_pk_mul_f32 v[26:27], v[8:9], v[56:57]
	s_cbranch_execnz .LBB0_83

; __device__ __forceinline__ void conv_weight(const float* W, int ldw, int K, int Nphys, int Nvalid, int mode, const float* g, bf16_t* WT, LAS float* scr, int gw, int NGW, int lane, int& rot) {
;     ...
;     for (int it = g0; it < items; it += NGW) {
;         const int kb = it / nblk, nb = it % nblk, k0 = 64 * kb, n0 = 32 * nb;
;         const int prow = n0 + (lane & 31); const bool ok = prow < Nvalid; const int col = ok ? colmap(mode, prow) : 0;
;         float wv_[32];
; #pragma unroll
;         for (int i = 0; i < 32; ++i) { const int kk = 2 * i + (lane >> 5); wv_[i] = ok ? W[(size_t)(k0 + kk) * ldw + col] : 0.f; }
.LBB0_114:
	s_ashr_i32 s10, s1, 31
	s_lshr_b32 s10, s10, 27
	s_add_i32 s10, s1, s10
	s_ashr_i32 s11, s10, 5
	s_lshl_b32 s10, s11, 6
	s_lshl_b32 s11, s11, 10
	s_sub_i32 s12, s14, s11
	v_add_u32_e32 v4, s12, v7
	v_cmp_gt_i32_e32 vcc, s16, v4
	v_or_b32_e32 v8, s10, v10
	v_mov_b32_e32 v9, 0
	v_cndmask_b32_e32 v4, 0, v4, vcc
	v_ashrrev_i32_e32 v5, 31, v4
	v_lshl_add_u64 v[4:5], v[4:5], 2, s[4:5]
	s_and_saveexec_b64 s[12:13], vcc
	s_cbranch_execz .LBB0_116
	v_ashrrev_i32_e32 v9, 31, v8
	v_lshlrev_b64 v[14:15], 12, v[8:9]
	v_lshl_add_u64 v[14:15], v[4:5], 0, v[14:15]
	global_load_dword v9, v[14:15], off nt
.LBB0_116:
	s_or_b64 exec, exec, s[12:13]
	v_mov_b32_e32 v14, 0
	v_mov_b32_e32 v15, 0
	s_and_saveexec_b64 s[12:13], vcc
	s_cbranch_execz .LBB0_118
	v_or_b32_e32 v16, 2, v8
	v_ashrrev_i32_e32 v17, 31, v16
	v_lshlrev_b64 v[16:17], 12, v[16:17]
	v_lshl_add_u64 v[16:17], v[4:5], 0, v[16:17]
	global_load_dword v15, v[16:17], off nt
.LBB0_118:
	s_or_b64 exec, exec, s[12:13]
	s_and_saveexec_b64 s[12:13], vcc
	s_cbranch_execz .LBB0_120
	v_or_b32_e32 v16, 4, v8
	v_ashrrev_i32_e32 v17, 31, v16
	v_lshlrev_b64 v[16:17], 12, v[16:17]
	v_lshl_add_u64 v[16:17], v[4:5], 0, v[16:17]
	global_load_dword v14, v[16:17], off nt
.LBB0_120:
	s_or_b64 exec, exec, s[12:13]
	v_mov_b32_e32 v16, 0
	v_mov_b32_e32 v17, 0
	s_and_saveexec_b64 s[12:13], vcc
	s_cbranch_execz .LBB0_122
	v_or_b32_e32 v20, 6, v8
	v_ashrrev_i32_e32 v21, 31, v20
	v_lshlrev_b64 v[20:21], 12, v[20:21]
	v_lshl_add_u64 v[20:21], v[4:5], 0, v[20:21]
	global_load_dword v17, v[20:21], off nt
.LBB0_122:
	s_or_b64 exec, exec, s[12:13]
	s_and_saveexec_b64 s[12:13], vcc
	s_cbranch_execz .LBB0_124
	v_or_b32_e32 v20, 8, v8
	v_ashrrev_i32_e32 v21, 31, v20
	v_lshlrev_b64 v[20:21], 12, v[20:21]
	v_lshl_add_u64 v[20:21], v[4:5], 0, v[20:21]
	global_load_dword v16, v[20:21], off nt
.LBB0_124:
	s_or_b64 exec, exec, s[12:13]
	v_mov_b32_e32 v20, 0
	v_mov_b32_e32 v21, 0
	s_and_saveexec_b64 s[12:13], vcc
	s_cbranch_execz .LBB0_126
	v_or_b32_e32 v22, 10, v8
	v_ashrrev_i32_e32 v23, 31, v22
	v_lshlrev_b64 v[22:23], 12, v[22:23]
	v_lshl_add_u64 v[22:23], v[4:5], 0, v[22:23]
	global_load_dword v21, v[22:23], off nt
.LBB0_126:
	s_or_b64 exec, exec, s[12:13]
	s_and_saveexec_b64 s[12:13], vcc
	s_cbranch_execz .LBB0_128
	v_or_b32_e32 v22, 12, v8
	v_ashrrev_i32_e32 v23, 31, v22
	v_lshlrev_b64 v[22:23], 12, v[22:23]
	v_lshl_add_u64 v[22:23], v[4:5], 0, v[22:23]
	global_load_dword v20, v[22:23], off nt
.LBB0_128:
	s_or_b64 exec, exec, s[12:13]
	v_mov_b32_e32 v22, 0
	v_mov_b32_e32 v23, 0
	s_and_saveexec_b64 s[12:13], vcc
	s_cbranch_execz .LBB0_130
	v_or_b32_e32 v24, 14, v8
	v_ashrrev_i32_e32 v25, 31, v24
	v_lshlrev_b64 v[24:25], 12, v[24:25]
	v_lshl_add_u64 v[24:25], v[4:5], 0, v[24:25]
	global_load_dword v23, v[24:25], off nt
.LBB0_130:
	s_or_b64 exec, exec, s[12:13]
	s_and_saveexec_b64 s[12:13], vcc
	s_cbranch_execz .LBB0_132
	v_or_b32_e32 v24, 16, v8
	v_ashrrev_i32_e32 v25, 31, v24
	v_lshlrev_b64 v[24:25], 12, v[24:25]
	v_lshl_add_u64 v[24:25], v[4:5], 0, v[24:25]
	global_load_dword v22, v[24:25], off nt
.LBB0_132:
	s_or_b64 exec, exec, s[12:13]
	v_mov_b32_e32 v24, 0
	v_mov_b32_e32 v25, 0
	s_and_saveexec_b64 s[12:13], vcc
	s_cbranch_execz .LBB0_134
	v_or_b32_e32 v26, 18, v8
	v_ashrrev_i32_e32 v27, 31, v26
	v_lshlrev_b64 v[26:27], 12, v[26:27]
	v_lshl_add_u64 v[26:27], v[4:5], 0, v[26:27]
	global_load_dword v25, v[26:27], off nt
.LBB0_134:
	s_or_b64 exec, exec, s[12:13]
	s_and_saveexec_b64 s[12:13], vcc
	s_cbranch_execz .LBB0_136
	v_or_b32_e32 v26, 20, v8
	v_ashrrev_i32_e32 v27, 31, v26
	v_lshlrev_b64 v[26:27], 12, v[26:27]
	v_lshl_add_u64 v[26:27], v[4:5], 0, v[26:27]
	global_load_dword v24, v[26:27], off nt
.LBB0_136:
	s_or_b64 exec, exec, s[12:13]
	v_mov_b32_e32 v26, 0
	v_mov_b32_e32 v27, 0
	s_and_saveexec_b64 s[12:13], vcc
	s_cbranch_execz .LBB0_138
	v_or_b32_e32 v28, 22, v8
	v_ashrrev_i32_e32 v29, 31, v28
	v_lshlrev_b64 v[28:29], 12, v[28:29]
	v_lshl_add_u64 v[28:29], v[4:5], 0, v[28:29]
	global_load_dword v27, v[28:29], off nt
.LBB0_138:
	s_or_b64 exec, exec, s[12:13]
	s_and_saveexec_b64 s[12:13], vcc
	s_cbranch_execz .LBB0_140
	v_or_b32_e32 v28, 24, v8
	v_ashrrev_i32_e32 v29, 31, v28
	v_lshlrev_b64 v[28:29], 12, v[28:29]
	v_lshl_add_u64 v[28:29], v[4:5], 0, v[28:29]
	global_load_dword v26, v[28:29], off nt
.LBB0_140:
	s_or_b64 exec, exec, s[12:13]
	v_mov_b32_e32 v28, 0
	v_mov_b32_e32 v29, 0
	s_and_saveexec_b64 s[12:13], vcc
	s_cbranch_execz .LBB0_142
	v_or_b32_e32 v30, 26, v8
	v_ashrrev_i32_e32 v31, 31, v30
	v_lshlrev_b64 v[30:31], 12, v[30:31]
	v_lshl_add_u64 v[30:31], v[4:5], 0, v[30:31]
	global_load_dword v29, v[30:31], off nt
.LBB0_142:
	s_or_b64 exec, exec, s[12:13]
	s_and_saveexec_b64 s[12:13], vcc
	s_cbranch_execz .LBB0_144
	v_or_b32_e32 v30, 28, v8
	v_ashrrev_i32_e32 v31, 31, v30
	v_lshlrev_b64 v[30:31], 12, v[30:31]
	v_lshl_add_u64 v[30:31], v[4:5], 0, v[30:31]
	global_load_dword v28, v[30:31], off nt
; __device__ __forceinline__ void conv_weight(const float* W, int ldw, int K, int Nphys, int Nvalid, int mode, const float* g, bf16_t* WT, LAS float* scr, int gw, int NGW, int lane, int& rot) {
;     ...
;         for (int i = 0; i < 32; ++i) { const int kk = 2 * i + (lane >> 5); wv_[i] = ok ? W[(size_t)(k0 + kk) * ldw + col] : 0.f; }
.LBB0_144:
	s_or_b64 exec, exec, s[12:13]
	v_mov_b32_e32 v30, 0
	v_mov_b32_e32 v31, 0
	s_and_saveexec_b64 s[12:13], vcc
	s_cbranch_execz .LBB0_146
	v_or_b32_e32 v32, 30, v8
	v_ashrrev_i32_e32 v33, 31, v32
	v_lshlrev_b64 v[32:33], 12, v[32:33]
	v_lshl_add_u64 v[32:33], v[4:5], 0, v[32:33]
	global_load_dword v31, v[32:33], off nt
.LBB0_146:
	s_or_b64 exec, exec, s[12:13]
	s_and_saveexec_b64 s[12:13], vcc
	s_cbranch_execz .LBB0_148
	v_or_b32_e32 v32, 32, v8
	v_ashrrev_i32_e32 v33, 31, v32
	v_lshlrev_b64 v[32:33], 12, v[32:33]
	v_lshl_add_u64 v[32:33], v[4:5], 0, v[32:33]
	global_load_dword v30, v[32:33], off nt
.LBB0_148:
	s_or_b64 exec, exec, s[12:13]
	v_mov_b32_e32 v32, 0
	v_mov_b32_e32 v33, 0
	s_and_saveexec_b64 s[12:13], vcc
	s_cbranch_execz .LBB0_150
	v_or_b32_e32 v36, 34, v8
	v_ashrrev_i32_e32 v37, 31, v36
	v_lshlrev_b64 v[36:37], 12, v[36:37]
	v_lshl_add_u64 v[36:37], v[4:5], 0, v[36:37]
	global_load_dword v33, v[36:37], off nt
.LBB0_150:
	s_or_b64 exec, exec, s[12:13]
	s_and_saveexec_b64 s[12:13], vcc
	s_cbranch_execz .LBB0_152
	v_or_b32_e32 v36, 36, v8
	v_ashrrev_i32_e32 v37, 31, v36
	v_lshlrev_b64 v[36:37], 12, v[36:37]
	v_lshl_add_u64 v[36:37], v[4:5], 0, v[36:37]
	global_load_dword v32, v[36:37], off nt
.LBB0_152:
	s_or_b64 exec, exec, s[12:13]
	v_mov_b32_e32 v36, 0
	v_mov_b32_e32 v37, 0
	s_and_saveexec_b64 s[12:13], vcc
	s_cbranch_execz .LBB0_154
	v_or_b32_e32 v38, 38, v8
	v_ashrrev_i32_e32 v39, 31, v38
	v_lshlrev_b64 v[38:39], 12, v[38:39]
	v_lshl_add_u64 v[38:39], v[4:5], 0, v[38:39]
	global_load_dword v37, v[38:39], off nt
.LBB0_154:
	s_or_b64 exec, exec, s[12:13]
	s_and_saveexec_b64 s[12:13], vcc
	s_cbranch_execz .LBB0_156
	v_or_b32_e32 v38, 40, v8
	v_ashrrev_i32_e32 v39, 31, v38
	v_lshlrev_b64 v[38:39], 12, v[38:39]
	v_lshl_add_u64 v[38:39], v[4:5], 0, v[38:39]
	global_load_dword v36, v[38:39], off nt
.LBB0_156:
	s_or_b64 exec, exec, s[12:13]
	v_mov_b32_e32 v38, 0
	v_mov_b32_e32 v39, 0
	s_and_saveexec_b64 s[12:13], vcc
	s_cbranch_execz .LBB0_158
	v_or_b32_e32 v40, 42, v8
	v_ashrrev_i32_e32 v41, 31, v40
	v_lshlrev_b64 v[40:41], 12, v[40:41]
	v_lshl_add_u64 v[40:41], v[4:5], 0, v[40:41]
	global_load_dword v39, v[40:41], off nt
.LBB0_158:
	s_or_b64 exec, exec, s[12:13]
	s_and_saveexec_b64 s[12:13], vcc
	s_cbranch_execz .LBB0_160
	v_or_b32_e32 v40, 44, v8
	v_ashrrev_i32_e32 v41, 31, v40
	v_lshlrev_b64 v[40:41], 12, v[40:41]
	v_lshl_add_u64 v[40:41], v[4:5], 0, v[40:41]
	global_load_dword v38, v[40:41], off nt
.LBB0_160:
	s_or_b64 exec, exec, s[12:13]
	v_mov_b32_e32 v40, 0
	v_mov_b32_e32 v41, 0
	s_and_saveexec_b64 s[12:13], vcc
	s_cbranch_execz .LBB0_162
	v_or_b32_e32 v42, 46, v8
	v_ashrrev_i32_e32 v43, 31, v42
	v_lshlrev_b64 v[42:43], 12, v[42:43]
	v_lshl_add_u64 v[42:43], v[4:5], 0, v[42:43]
	global_load_dword v41, v[42:43], off nt
.LBB0_162:
	s_or_b64 exec, exec, s[12:13]
	s_and_saveexec_b64 s[12:13], vcc
	s_cbranch_execz .LBB0_164
	v_or_b32_e32 v42, 48, v8
	v_ashrrev_i32_e32 v43, 31, v42
	v_lshlrev_b64 v[42:43], 12, v[42:43]
	v_lshl_add_u64 v[42:43], v[4:5], 0, v[42:43]
	global_load_dword v40, v[42:43], off nt
.LBB0_164:
	s_or_b64 exec, exec, s[12:13]
	v_mov_b32_e32 v42, 0
	v_mov_b32_e32 v43, 0
	s_and_saveexec_b64 s[12:13], vcc
	s_cbranch_execz .LBB0_166
	v_or_b32_e32 v44, 50, v8
	v_ashrrev_i32_e32 v45, 31, v44
	v_lshlrev_b64 v[44:45], 12, v[44:45]
	v_lshl_add_u64 v[44:45], v[4:5], 0, v[44:45]
	global_load_dword v43, v[44:45], off nt
.LBB0_166:
	s_or_b64 exec, exec, s[12:13]
	s_and_saveexec_b64 s[12:13], vcc
	s_cbranch_execz .LBB0_168
	v_or_b32_e32 v44, 52, v8
	v_ashrrev_i32_e32 v45, 31, v44
	v_lshlrev_b64 v[44:45], 12, v[44:45]
	v_lshl_add_u64 v[44:45], v[4:5], 0, v[44:45]
	global_load_dword v42, v[44:45], off nt
.LBB0_168:
	s_or_b64 exec, exec, s[12:13]
	v_mov_b32_e32 v44, 0
	v_mov_b32_e32 v45, 0
	s_and_saveexec_b64 s[12:13], vcc
	s_cbranch_execz .LBB0_170
	v_or_b32_e32 v46, 54, v8
	v_ashrrev_i32_e32 v47, 31, v46
	v_lshlrev_b64 v[46:47], 12, v[46:47]
	v_lshl_add_u64 v[46:47], v[4:5], 0, v[46:47]
	global_load_dword v45, v[46:47], off nt
.LBB0_170:
	s_or_b64 exec, exec, s[12:13]
	s_and_saveexec_b64 s[12:13], vcc
	s_cbranch_execz .LBB0_172
	v_or_b32_e32 v46, 56, v8
	v_ashrrev_i32_e32 v47, 31, v46
	v_lshlrev_b64 v[46:47], 12, v[46:47]
	v_lshl_add_u64 v[46:47], v[4:5], 0, v[46:47]
	global_load_dword v44, v[46:47], off nt
.LBB0_172:
	s_or_b64 exec, exec, s[12:13]
	v_mov_b32_e32 v46, 0
	v_mov_b32_e32 v47, 0
	s_and_saveexec_b64 s[12:13], vcc
	s_cbranch_execz .LBB0_175
	v_or_b32_e32 v48, 58, v8
	v_ashrrev_i32_e32 v49, 31, v48
	v_lshlrev_b64 v[48:49], 12, v[48:49]
	v_lshl_add_u64 v[48:49], v[4:5], 0, v[48:49]
	global_load_dword v47, v[48:49], off nt
	s_or_b64 exec, exec, s[12:13]
	s_and_saveexec_b64 s[12:13], vcc
	s_cbranch_execnz .LBB0_176

; __device__ __forceinline__ void conv_weight(const float* W, int ldw, int K, int Nphys, int Nvalid, int mode, const float* g, bf16_t* WT, LAS float* scr, int gw, int NGW, int lane, int& rot) {
;     ...
;         for (int i = 0; i < 32; ++i) { const int kk = 2 * i + (lane >> 5); wv_[i] = ok ? W[(size_t)(k0 + kk) * ldw + col] : 0.f; }
.LBB0_176:
	v_or_b32_e32 v48, 60, v8
	v_ashrrev_i32_e32 v49, 31, v48
	v_lshlrev_b64 v[48:49], 12, v[48:49]
	v_lshl_add_u64 v[48:49], v[4:5], 0, v[48:49]
	global_load_dword v46, v[48:49], off nt
	s_or_b64 exec, exec, s[12:13]
	v_mov_b32_e32 v48, 0
	s_and_saveexec_b64 s[12:13], vcc
	s_cbranch_execz .LBB0_113
.LBB0_177:
	v_or_b32_e32 v48, 62, v8
	v_ashrrev_i32_e32 v49, 31, v48
	v_lshlrev_b64 v[48:49], 12, v[48:49]
	v_lshl_add_u64 v[4:5], v[4:5], 0, v[48:49]
	global_load_dword v48, v[4:5], off nt
	s_branch .LBB0_113

; __device__ __forceinline__ void conv_weight(const float* W, int ldw, int K, int Nphys, int Nvalid, int mode, const float* g, bf16_t* WT, LAS float* scr, int gw, int NGW, int lane, int& rot) {
;     ...
;     for (int it = g0; it < items; it += NGW) {
;         const int kb = it / nblk, nb = it % nblk, k0 = 64 * kb, n0 = 32 * nb;
;         const int prow = n0 + (lane & 31); const bool ok = prow < Nvalid; const int col = ok ? colmap(mode, prow) : 0;
;         float wv_[32];
; #pragma unroll
;         for (int i = 0; i < 32; ++i) { const int kk = 2 * i + (lane >> 5); wv_[i] = ok ? W[(size_t)(k0 + kk) * ldw + col] : 0.f; }
.LBB0_184:
	s_ashr_i32 s4, s1, 31
	s_lshr_b32 s4, s4, 29
	s_add_i32 s4, s1, s4
	s_ashr_i32 s4, s4, 3
	s_lshl_b32 s25, s4, 8
	s_lshl_b32 s16, s4, 6
	s_sub_i32 s4, s20, s25
	v_add_u32_e32 v8, s4, v34
	v_cmp_gt_i32_e32 vcc, s22, v8
	v_or_b32_e32 v12, s16, v6
	v_ashrrev_i32_e32 v13, 31, v12
	v_cndmask_b32_e32 v8, 0, v8, vcc
	v_ashrrev_i32_e32 v9, 31, v8
	v_lshl_add_u64 v[16:17], v[8:9], 2, s[10:11]
	v_mov_b32_e32 v44, 0
	s_and_saveexec_b64 s[4:5], vcc
	s_cbranch_execz .LBB0_186
	v_lshlrev_b64 v[8:9], 10, v[12:13]
	v_lshl_add_u64 v[8:9], v[16:17], 0, v[8:9]
	global_load_dword v44, v[8:9], off nt
.LBB0_186:
	s_or_b64 exec, exec, s[4:5]
	v_mov_b32_e32 v8, 0
	v_mov_b32_e32 v46, 0
	s_and_saveexec_b64 s[4:5], vcc
	s_cbranch_execz .LBB0_188
	v_or_b32_e32 v10, 2, v12
	v_ashrrev_i32_e32 v11, 31, v10
	v_lshlrev_b64 v[10:11], 10, v[10:11]
	v_lshl_add_u64 v[10:11], v[16:17], 0, v[10:11]
	global_load_dword v46, v[10:11], off nt
.LBB0_188:
	s_or_b64 exec, exec, s[4:5]
	s_and_saveexec_b64 s[4:5], vcc
	s_cbranch_execz .LBB0_190
	v_or_b32_e32 v8, 4, v12
	v_ashrrev_i32_e32 v9, 31, v8
	v_lshlrev_b64 v[8:9], 10, v[8:9]
	v_lshl_add_u64 v[8:9], v[16:17], 0, v[8:9]
	global_load_dword v8, v[8:9], off nt
.LBB0_190:
	s_or_b64 exec, exec, s[4:5]
	v_mov_b32_e32 v43, 0
	v_mov_b32_e32 v9, 0
	s_and_saveexec_b64 s[4:5], vcc
	s_cbranch_execz .LBB0_192
	v_or_b32_e32 v10, 6, v12
	v_ashrrev_i32_e32 v11, 31, v10
	v_lshlrev_b64 v[10:11], 10, v[10:11]
	v_lshl_add_u64 v[10:11], v[16:17], 0, v[10:11]
	global_load_dword v9, v[10:11], off nt
.LBB0_192:
	s_or_b64 exec, exec, s[4:5]
	s_and_saveexec_b64 s[4:5], vcc
	s_cbranch_execz .LBB0_194
	v_or_b32_e32 v10, 8, v12
	v_ashrrev_i32_e32 v11, 31, v10
	v_lshlrev_b64 v[10:11], 10, v[10:11]
	v_lshl_add_u64 v[10:11], v[16:17], 0, v[10:11]
	global_load_dword v43, v[10:11], off nt
.LBB0_194:
	s_or_b64 exec, exec, s[4:5]
	v_mov_b32_e32 v10, 0
	v_mov_b32_e32 v48, 0
	s_and_saveexec_b64 s[4:5], vcc
	s_cbranch_execz .LBB0_196
	v_or_b32_e32 v14, 10, v12
	v_ashrrev_i32_e32 v15, 31, v14
	v_lshlrev_b64 v[14:15], 10, v[14:15]
	v_lshl_add_u64 v[14:15], v[16:17], 0, v[14:15]
	global_load_dword v48, v[14:15], off nt
.LBB0_196:
	s_or_b64 exec, exec, s[4:5]
	s_and_saveexec_b64 s[4:5], vcc
	s_cbranch_execz .LBB0_198
	v_or_b32_e32 v10, 12, v12
	v_ashrrev_i32_e32 v11, 31, v10
	v_lshlrev_b64 v[10:11], 10, v[10:11]
	v_lshl_add_u64 v[10:11], v[16:17], 0, v[10:11]
	global_load_dword v10, v[10:11], off nt
.LBB0_198:
	s_or_b64 exec, exec, s[4:5]
	v_mov_b32_e32 v45, 0
	v_mov_b32_e32 v11, 0
	s_and_saveexec_b64 s[4:5], vcc
	s_cbranch_execz .LBB0_200
	v_or_b32_e32 v14, 14, v12
	v_ashrrev_i32_e32 v15, 31, v14
	v_lshlrev_b64 v[14:15], 10, v[14:15]
	v_lshl_add_u64 v[14:15], v[16:17], 0, v[14:15]
	global_load_dword v11, v[14:15], off nt
.LBB0_200:
	s_or_b64 exec, exec, s[4:5]
	s_and_saveexec_b64 s[4:5], vcc
	s_cbranch_execz .LBB0_202
	v_or_b32_e32 v14, 16, v12
	v_ashrrev_i32_e32 v15, 31, v14
	v_lshlrev_b64 v[14:15], 10, v[14:15]
	v_lshl_add_u64 v[14:15], v[16:17], 0, v[14:15]
	global_load_dword v45, v[14:15], off nt
.LBB0_202:
	s_or_b64 exec, exec, s[4:5]
	v_mov_b32_e32 v14, 0
	v_mov_b32_e32 v50, 0
	s_and_saveexec_b64 s[4:5], vcc
	s_cbranch_execz .LBB0_204
	v_or_b32_e32 v20, 18, v12
	v_ashrrev_i32_e32 v21, 31, v20
	v_lshlrev_b64 v[20:21], 10, v[20:21]
	v_lshl_add_u64 v[20:21], v[16:17], 0, v[20:21]
	global_load_dword v50, v[20:21], off nt
.LBB0_204:
	s_or_b64 exec, exec, s[4:5]
	s_and_saveexec_b64 s[4:5], vcc
	s_cbranch_execz .LBB0_206
	v_or_b32_e32 v14, 20, v12
	v_ashrrev_i32_e32 v15, 31, v14
	v_lshlrev_b64 v[14:15], 10, v[14:15]
	v_lshl_add_u64 v[14:15], v[16:17], 0, v[14:15]
	global_load_dword v14, v[14:15], off nt
.LBB0_206:
	s_or_b64 exec, exec, s[4:5]
	v_mov_b32_e32 v47, 0
	v_mov_b32_e32 v15, 0
	s_and_saveexec_b64 s[4:5], vcc
	s_cbranch_execz .LBB0_208
	v_or_b32_e32 v20, 22, v12
	v_ashrrev_i32_e32 v21, 31, v20
	v_lshlrev_b64 v[20:21], 10, v[20:21]
	v_lshl_add_u64 v[20:21], v[16:17], 0, v[20:21]
	global_load_dword v15, v[20:21], off nt
.LBB0_208:
	s_or_b64 exec, exec, s[4:5]
	s_and_saveexec_b64 s[4:5], vcc
	s_cbranch_execz .LBB0_210
	v_or_b32_e32 v20, 24, v12
	v_ashrrev_i32_e32 v21, 31, v20
	v_lshlrev_b64 v[20:21], 10, v[20:21]
	v_lshl_add_u64 v[20:21], v[16:17], 0, v[20:21]
	global_load_dword v47, v[20:21], off nt
.LBB0_210:
	s_or_b64 exec, exec, s[4:5]
	v_mov_b32_e32 v20, 0
	v_mov_b32_e32 v52, 0
	s_and_saveexec_b64 s[4:5], vcc
	s_cbranch_execz .LBB0_212
	v_or_b32_e32 v22, 26, v12
	v_ashrrev_i32_e32 v23, 31, v22
	v_lshlrev_b64 v[22:23], 10, v[22:23]
	v_lshl_add_u64 v[22:23], v[16:17], 0, v[22:23]
	global_load_dword v52, v[22:23], off nt
.LBB0_212:
	s_or_b64 exec, exec, s[4:5]
	s_and_saveexec_b64 s[4:5], vcc
	s_cbranch_execz .LBB0_214
	v_or_b32_e32 v20, 28, v12
	v_ashrrev_i32_e32 v21, 31, v20
	v_lshlrev_b64 v[20:21], 10, v[20:21]
	v_lshl_add_u64 v[20:21], v[16:17], 0, v[20:21]
	global_load_dword v20, v[20:21], off nt
; __device__ __forceinline__ void conv_weight(const float* W, int ldw, int K, int Nphys, int Nvalid, int mode, const float* g, bf16_t* WT, LAS float* scr, int gw, int NGW, int lane, int& rot) {
;     ...
;         for (int i = 0; i < 32; ++i) { const int kk = 2 * i + (lane >> 5); wv_[i] = ok ? W[(size_t)(k0 + kk) * ldw + col] : 0.f; }
.LBB0_214:
	s_or_b64 exec, exec, s[4:5]
	v_mov_b32_e32 v49, 0
	v_mov_b32_e32 v21, 0
	s_and_saveexec_b64 s[4:5], vcc
	s_cbranch_execz .LBB0_216
	v_or_b32_e32 v22, 30, v12
	v_ashrrev_i32_e32 v23, 31, v22
	v_lshlrev_b64 v[22:23], 10, v[22:23]
	v_lshl_add_u64 v[22:23], v[16:17], 0, v[22:23]
	global_load_dword v21, v[22:23], off nt
.LBB0_216:
	s_or_b64 exec, exec, s[4:5]
	s_and_saveexec_b64 s[4:5], vcc
	s_cbranch_execz .LBB0_218
	v_or_b32_e32 v22, 32, v12
	v_ashrrev_i32_e32 v23, 31, v22
	v_lshlrev_b64 v[22:23], 10, v[22:23]
	v_lshl_add_u64 v[22:23], v[16:17], 0, v[22:23]
	global_load_dword v49, v[22:23], off nt
.LBB0_218:
	s_or_b64 exec, exec, s[4:5]
	v_mov_b32_e32 v22, 0
	v_mov_b32_e32 v54, 0
	s_and_saveexec_b64 s[4:5], vcc
	s_cbranch_execz .LBB0_220
	v_or_b32_e32 v24, 34, v12
	v_ashrrev_i32_e32 v25, 31, v24
	v_lshlrev_b64 v[24:25], 10, v[24:25]
	v_lshl_add_u64 v[24:25], v[16:17], 0, v[24:25]
	global_load_dword v54, v[24:25], off nt
.LBB0_220:
	s_or_b64 exec, exec, s[4:5]
	s_and_saveexec_b64 s[4:5], vcc
	s_cbranch_execz .LBB0_222
	v_or_b32_e32 v22, 36, v12
	v_ashrrev_i32_e32 v23, 31, v22
	v_lshlrev_b64 v[22:23], 10, v[22:23]
	v_lshl_add_u64 v[22:23], v[16:17], 0, v[22:23]
	global_load_dword v22, v[22:23], off nt
.LBB0_222:
	s_or_b64 exec, exec, s[4:5]
	v_mov_b32_e32 v51, 0
	v_mov_b32_e32 v23, 0
	s_and_saveexec_b64 s[4:5], vcc
	s_cbranch_execz .LBB0_224
	v_or_b32_e32 v24, 38, v12
	v_ashrrev_i32_e32 v25, 31, v24
	v_lshlrev_b64 v[24:25], 10, v[24:25]
	v_lshl_add_u64 v[24:25], v[16:17], 0, v[24:25]
	global_load_dword v23, v[24:25], off nt
.LBB0_224:
	s_or_b64 exec, exec, s[4:5]
	s_and_saveexec_b64 s[4:5], vcc
	s_cbranch_execz .LBB0_226
	v_or_b32_e32 v24, 40, v12
	v_ashrrev_i32_e32 v25, 31, v24
	v_lshlrev_b64 v[24:25], 10, v[24:25]
	v_lshl_add_u64 v[24:25], v[16:17], 0, v[24:25]
	global_load_dword v51, v[24:25], off nt
.LBB0_226:
	s_or_b64 exec, exec, s[4:5]
	v_mov_b32_e32 v24, 0
	v_mov_b32_e32 v56, 0
	s_and_saveexec_b64 s[4:5], vcc
	s_cbranch_execz .LBB0_228
	v_or_b32_e32 v26, 42, v12
	v_ashrrev_i32_e32 v27, 31, v26
	v_lshlrev_b64 v[26:27], 10, v[26:27]
	v_lshl_add_u64 v[26:27], v[16:17], 0, v[26:27]
	global_load_dword v56, v[26:27], off nt
.LBB0_228:
	s_or_b64 exec, exec, s[4:5]
	s_and_saveexec_b64 s[4:5], vcc
	s_cbranch_execz .LBB0_230
	v_or_b32_e32 v24, 44, v12
	v_ashrrev_i32_e32 v25, 31, v24
	v_lshlrev_b64 v[24:25], 10, v[24:25]
	v_lshl_add_u64 v[24:25], v[16:17], 0, v[24:25]
	global_load_dword v24, v[24:25], off nt
.LBB0_230:
	s_or_b64 exec, exec, s[4:5]
	v_mov_b32_e32 v53, 0
	v_mov_b32_e32 v25, 0
	s_and_saveexec_b64 s[4:5], vcc
	s_cbranch_execz .LBB0_232
	v_or_b32_e32 v26, 46, v12
	v_ashrrev_i32_e32 v27, 31, v26
	v_lshlrev_b64 v[26:27], 10, v[26:27]
	v_lshl_add_u64 v[26:27], v[16:17], 0, v[26:27]
	global_load_dword v25, v[26:27], off nt
.LBB0_232:
	s_or_b64 exec, exec, s[4:5]
	s_and_saveexec_b64 s[4:5], vcc
	s_cbranch_execz .LBB0_234
	v_or_b32_e32 v26, 48, v12
	v_ashrrev_i32_e32 v27, 31, v26
	v_lshlrev_b64 v[26:27], 10, v[26:27]
	v_lshl_add_u64 v[26:27], v[16:17], 0, v[26:27]
	global_load_dword v53, v[26:27], off nt
.LBB0_234:
	s_or_b64 exec, exec, s[4:5]
	v_mov_b32_e32 v26, 0
	v_mov_b32_e32 v57, 0
	s_and_saveexec_b64 s[4:5], vcc
	s_cbranch_execz .LBB0_236
	v_or_b32_e32 v28, 50, v12
	v_ashrrev_i32_e32 v29, 31, v28
	v_lshlrev_b64 v[28:29], 10, v[28:29]
	v_lshl_add_u64 v[28:29], v[16:17], 0, v[28:29]
	global_load_dword v57, v[28:29], off nt
.LBB0_236:
	s_or_b64 exec, exec, s[4:5]
	s_and_saveexec_b64 s[4:5], vcc
	s_cbranch_execz .LBB0_238
	v_or_b32_e32 v26, 52, v12
	v_ashrrev_i32_e32 v27, 31, v26
	v_lshlrev_b64 v[26:27], 10, v[26:27]
	v_lshl_add_u64 v[26:27], v[16:17], 0, v[26:27]
	global_load_dword v26, v[26:27], off nt
.LBB0_238:
	s_or_b64 exec, exec, s[4:5]
	v_mov_b32_e32 v55, 0
	v_mov_b32_e32 v27, 0
	s_and_saveexec_b64 s[4:5], vcc
	s_cbranch_execz .LBB0_240
	v_or_b32_e32 v28, 54, v12
	v_ashrrev_i32_e32 v29, 31, v28
	v_lshlrev_b64 v[28:29], 10, v[28:29]
	v_lshl_add_u64 v[28:29], v[16:17], 0, v[28:29]
	global_load_dword v27, v[28:29], off nt
.LBB0_240:
	s_or_b64 exec, exec, s[4:5]
	s_and_saveexec_b64 s[4:5], vcc
	s_cbranch_execz .LBB0_242
	v_or_b32_e32 v28, 56, v12
	v_ashrrev_i32_e32 v29, 31, v28
	v_lshlrev_b64 v[28:29], 10, v[28:29]
	v_lshl_add_u64 v[28:29], v[16:17], 0, v[28:29]
	global_load_dword v55, v[28:29], off nt
.LBB0_242:
	s_or_b64 exec, exec, s[4:5]
	v_mov_b32_e32 v28, 0
	v_mov_b32_e32 v58, 0
	s_and_saveexec_b64 s[4:5], vcc
	s_cbranch_execz .LBB0_269
	v_or_b32_e32 v58, 58, v12
	v_ashrrev_i32_e32 v59, 31, v58
	v_lshlrev_b64 v[58:59], 10, v[58:59]
	v_lshl_add_u64 v[58:59], v[16:17], 0, v[58:59]
	global_load_dword v58, v[58:59], off nt
	s_or_b64 exec, exec, s[4:5]
	s_and_saveexec_b64 s[4:5], vcc
	s_cbranch_execnz .LBB0_270

; __device__ __forceinline__ void conv_weight(const float* W, int ldw, int K, int Nphys, int Nvalid, int mode, const float* g, bf16_t* WT, LAS float* scr, int gw, int NGW, int lane, int& rot) {
;     ...
;         for (int i = 0; i < 32; ++i) { const int kk = 2 * i + (lane >> 5); wv_[i] = ok ? W[(size_t)(k0 + kk) * ldw + col] : 0.f; }
; #pragma unroll
;         for (int i = 0; i < 32; ++i) { const int kk = 2 * i + (lane >> 5); float v = wv_[i]; if (g) v *= g[k0 + kk]; scr[kk * 33 + (lane & 31)] = v; }
.LBB0_245:
	v_or_b32_e32 v60, 62, v12
	v_ashrrev_i32_e32 v61, 31, v60
	v_lshlrev_b64 v[60:61], 10, v[60:61]
	v_lshl_add_u64 v[16:17], v[16:17], 0, v[60:61]
	global_load_dword v29, v[16:17], off nt
.LBB0_246:
	s_or_b64 exec, exec, s[4:5]
	v_cndmask_b32_e64 v16, 0, 1, s[14:15]
	v_cmp_ne_u32_e64 s[4:5], 1, v16
	s_andn2_b64 vcc, exec, s[14:15]
	v_add_u32_e32 v16, v30, v37
	s_cbranch_vccnz .LBB0_271
	s_ashr_i32 s17, s16, 31
	v_lshl_add_u64 v[12:13], v[12:13], 2, s[12:13]
	v_lshl_add_u64 v[60:61], s[16:17], 0, v[6:7]
	v_lshl_add_u64 v[60:61], v[60:61], 2, s[12:13]
	global_load_dword v17, v[12:13], off nt
	global_load_dword v59, v[60:61], off offset:8
	global_load_dword v62, v[60:61], off offset:16
	global_load_dword v63, v[60:61], off offset:24
	s_waitcnt vmcnt(3)
	v_mul_f32_e32 v17, v44, v17
	s_waitcnt vmcnt(2)
	v_mul_f32_e32 v59, v46, v59
	ds_write2_b32 v16, v17, v59 offset1:66
	s_waitcnt vmcnt(0)
	v_pk_mul_f32 v[12:13], v[8:9], v[62:63]
	s_cbranch_execnz .LBB0_249

; __device__ __forceinline__ void conv_weight(const float* W, int ldw, int K, int Nphys, int Nvalid, int mode, const float* g, bf16_t* WT, LAS float* scr, int gw, int NGW, int lane, int& rot) {
;     ...
;         for (int i = 0; i < 32; ++i) { const int kk = 2 * i + (lane >> 5); wv_[i] = ok ? W[(size_t)(k0 + kk) * ldw + col] : 0.f; }
.LBB0_270:
	v_or_b32_e32 v28, 60, v12
	v_ashrrev_i32_e32 v29, 31, v28
	v_lshlrev_b64 v[28:29], 10, v[28:29]
	v_lshl_add_u64 v[28:29], v[16:17], 0, v[28:29]
	global_load_dword v28, v[28:29], off nt
	s_or_b64 exec, exec, s[4:5]
	v_mov_b32_e32 v29, 0
	s_and_saveexec_b64 s[4:5], vcc
	s_cbranch_execnz .LBB0_245
	s_branch .LBB0_246

; __device__ __forceinline__ void conv_weight(const float* W, int ldw, int K, int Nphys, int Nvalid, int mode, const float* g, bf16_t* WT, LAS float* scr, int gw, int NGW, int lane, int& rot) {
;     ...
;     for (int it = g0; it < items; it += NGW) {
;         const int kb = it / nblk, nb = it % nblk, k0 = 64 * kb, n0 = 32 * nb;
;         const int prow = n0 + (lane & 31); const bool ok = prow < Nvalid; const int col = ok ? colmap(mode, prow) : 0;
;         float wv_[32];
; #pragma unroll
;         for (int i = 0; i < 32; ++i) { const int kk = 2 * i + (lane >> 5); wv_[i] = ok ? W[(size_t)(k0 + kk) * ldw + col] : 0.f; }
.LBB0_285:
	s_ashr_i32 s12, s21, 31
	s_lshr_b32 s12, s12, 28
	s_add_i32 s12, s21, s12
	s_ashr_i32 s13, s12, 4
	s_lshl_b32 s12, s13, 6
	s_lshl_b32 s13, s13, 9
	s_sub_i32 s14, s16, s13
	v_add_u32_e32 v5, s14, v30
	v_cmp_gt_i32_e32 vcc, s1, v5
	v_or_b32_e32 v10, s12, v4
	v_mov_b32_e32 v13, 0
	v_cndmask_b32_e32 v8, 0, v5, vcc
	v_ashrrev_i32_e32 v9, 31, v8
	v_lshl_add_u64 v[8:9], v[8:9], 2, s[10:11]
	v_mov_b32_e32 v5, 0
	s_and_saveexec_b64 s[14:15], vcc
	s_cbranch_execz .LBB0_287
	v_ashrrev_i32_e32 v11, 31, v10
	v_lshlrev_b64 v[14:15], 11, v[10:11]
	v_lshl_add_u64 v[14:15], v[8:9], 0, v[14:15]
	global_load_dword v5, v[14:15], off nt
.LBB0_287:
	s_or_b64 exec, exec, s[14:15]
	s_and_saveexec_b64 s[14:15], vcc
	s_cbranch_execz .LBB0_289
	v_or_b32_e32 v14, 2, v10
	v_ashrrev_i32_e32 v15, 31, v14
	v_lshlrev_b64 v[14:15], 11, v[14:15]
	v_lshl_add_u64 v[14:15], v[8:9], 0, v[14:15]
	global_load_dword v13, v[14:15], off nt
.LBB0_289:
	s_or_b64 exec, exec, s[14:15]
	v_mov_b32_e32 v11, 0
	v_mov_b32_e32 v14, 0
	s_and_saveexec_b64 s[14:15], vcc
	s_cbranch_execz .LBB0_291
	v_or_b32_e32 v14, 4, v10
	v_ashrrev_i32_e32 v15, 31, v14
	v_lshlrev_b64 v[14:15], 11, v[14:15]
	v_lshl_add_u64 v[14:15], v[8:9], 0, v[14:15]
	global_load_dword v14, v[14:15], off nt
.LBB0_291:
	s_or_b64 exec, exec, s[14:15]
	s_and_saveexec_b64 s[14:15], vcc
	s_cbranch_execz .LBB0_293
	v_or_b32_e32 v16, 6, v10
	v_ashrrev_i32_e32 v17, 31, v16
	v_lshlrev_b64 v[16:17], 11, v[16:17]
	v_lshl_add_u64 v[16:17], v[8:9], 0, v[16:17]
	global_load_dword v11, v[16:17], off nt
.LBB0_293:
	s_or_b64 exec, exec, s[14:15]
	v_mov_b32_e32 v15, 0
	v_mov_b32_e32 v16, 0
	s_and_saveexec_b64 s[14:15], vcc
	s_cbranch_execz .LBB0_295
	v_or_b32_e32 v16, 8, v10
	v_ashrrev_i32_e32 v17, 31, v16
	v_lshlrev_b64 v[16:17], 11, v[16:17]
	v_lshl_add_u64 v[16:17], v[8:9], 0, v[16:17]
	global_load_dword v16, v[16:17], off nt
.LBB0_295:
	s_or_b64 exec, exec, s[14:15]
	s_and_saveexec_b64 s[14:15], vcc
	s_cbranch_execz .LBB0_297
	v_or_b32_e32 v20, 10, v10
	v_ashrrev_i32_e32 v21, 31, v20
	v_lshlrev_b64 v[20:21], 11, v[20:21]
	v_lshl_add_u64 v[20:21], v[8:9], 0, v[20:21]
	global_load_dword v15, v[20:21], off nt
.LBB0_297:
	s_or_b64 exec, exec, s[14:15]
	v_mov_b32_e32 v17, 0
	v_mov_b32_e32 v20, 0
	s_and_saveexec_b64 s[14:15], vcc
	s_cbranch_execz .LBB0_299
	v_or_b32_e32 v20, 12, v10
	v_ashrrev_i32_e32 v21, 31, v20
	v_lshlrev_b64 v[20:21], 11, v[20:21]
	v_lshl_add_u64 v[20:21], v[8:9], 0, v[20:21]
	global_load_dword v20, v[20:21], off nt
.LBB0_299:
	s_or_b64 exec, exec, s[14:15]
	s_and_saveexec_b64 s[14:15], vcc
	s_cbranch_execz .LBB0_301
	v_or_b32_e32 v22, 14, v10
	v_ashrrev_i32_e32 v23, 31, v22
	v_lshlrev_b64 v[22:23], 11, v[22:23]
	v_lshl_add_u64 v[22:23], v[8:9], 0, v[22:23]
	global_load_dword v17, v[22:23], off nt
.LBB0_301:
	s_or_b64 exec, exec, s[14:15]
	v_mov_b32_e32 v21, 0
	v_mov_b32_e32 v22, 0
	s_and_saveexec_b64 s[14:15], vcc
	s_cbranch_execz .LBB0_303
	v_or_b32_e32 v22, 16, v10
	v_ashrrev_i32_e32 v23, 31, v22
	v_lshlrev_b64 v[22:23], 11, v[22:23]
	v_lshl_add_u64 v[22:23], v[8:9], 0, v[22:23]
	global_load_dword v22, v[22:23], off nt
.LBB0_303:
	s_or_b64 exec, exec, s[14:15]
	s_and_saveexec_b64 s[14:15], vcc
	s_cbranch_execz .LBB0_305
	v_or_b32_e32 v24, 18, v10
	v_ashrrev_i32_e32 v25, 31, v24
	v_lshlrev_b64 v[24:25], 11, v[24:25]
	v_lshl_add_u64 v[24:25], v[8:9], 0, v[24:25]
	global_load_dword v21, v[24:25], off nt
.LBB0_305:
	s_or_b64 exec, exec, s[14:15]
	v_mov_b32_e32 v23, 0
	v_mov_b32_e32 v24, 0
	s_and_saveexec_b64 s[14:15], vcc
	s_cbranch_execz .LBB0_307
	v_or_b32_e32 v24, 20, v10
	v_ashrrev_i32_e32 v25, 31, v24
	v_lshlrev_b64 v[24:25], 11, v[24:25]
	v_lshl_add_u64 v[24:25], v[8:9], 0, v[24:25]
	global_load_dword v24, v[24:25], off nt
.LBB0_307:
	s_or_b64 exec, exec, s[14:15]
	s_and_saveexec_b64 s[14:15], vcc
	s_cbranch_execz .LBB0_309
	v_or_b32_e32 v26, 22, v10
	v_ashrrev_i32_e32 v27, 31, v26
	v_lshlrev_b64 v[26:27], 11, v[26:27]
	v_lshl_add_u64 v[26:27], v[8:9], 0, v[26:27]
	global_load_dword v23, v[26:27], off nt
.LBB0_309:
	s_or_b64 exec, exec, s[14:15]
	v_mov_b32_e32 v25, 0
	v_mov_b32_e32 v26, 0
	s_and_saveexec_b64 s[14:15], vcc
	s_cbranch_execz .LBB0_311
	v_or_b32_e32 v26, 24, v10
	v_ashrrev_i32_e32 v27, 31, v26
	v_lshlrev_b64 v[26:27], 11, v[26:27]
	v_lshl_add_u64 v[26:27], v[8:9], 0, v[26:27]
	global_load_dword v26, v[26:27], off nt
.LBB0_311:
	s_or_b64 exec, exec, s[14:15]
	s_and_saveexec_b64 s[14:15], vcc
	s_cbranch_execz .LBB0_313
	v_or_b32_e32 v28, 26, v10
	v_ashrrev_i32_e32 v29, 31, v28
	v_lshlrev_b64 v[28:29], 11, v[28:29]
	v_lshl_add_u64 v[28:29], v[8:9], 0, v[28:29]
	global_load_dword v25, v[28:29], off nt
.LBB0_313:
	s_or_b64 exec, exec, s[14:15]
	v_mov_b32_e32 v27, 0
	v_mov_b32_e32 v28, 0
	s_and_saveexec_b64 s[14:15], vcc
	s_cbranch_execz .LBB0_315
	v_or_b32_e32 v28, 28, v10
	v_ashrrev_i32_e32 v29, 31, v28
	v_lshlrev_b64 v[28:29], 11, v[28:29]
	v_lshl_add_u64 v[28:29], v[8:9], 0, v[28:29]
	global_load_dword v28, v[28:29], off nt
.LBB0_315:
	s_or_b64 exec, exec, s[14:15]
	s_and_saveexec_b64 s[14:15], vcc
	s_cbranch_execz .LBB0_317
	v_or_b32_e32 v40, 30, v10
	v_ashrrev_i32_e32 v41, 31, v40
	v_lshlrev_b64 v[40:41], 11, v[40:41]
	v_lshl_add_u64 v[40:41], v[8:9], 0, v[40:41]
	global_load_dword v27, v[40:41], off nt
; __device__ __forceinline__ void conv_weight(const float* W, int ldw, int K, int Nphys, int Nvalid, int mode, const float* g, bf16_t* WT, LAS float* scr, int gw, int NGW, int lane, int& rot) {
;     ...
;         for (int i = 0; i < 32; ++i) { const int kk = 2 * i + (lane >> 5); wv_[i] = ok ? W[(size_t)(k0 + kk) * ldw + col] : 0.f; }
.LBB0_317:
	s_or_b64 exec, exec, s[14:15]
	v_mov_b32_e32 v29, 0
	v_mov_b32_e32 v40, 0
	s_and_saveexec_b64 s[14:15], vcc
	s_cbranch_execz .LBB0_319
	v_or_b32_e32 v40, 32, v10
	v_ashrrev_i32_e32 v41, 31, v40
	v_lshlrev_b64 v[40:41], 11, v[40:41]
	v_lshl_add_u64 v[40:41], v[8:9], 0, v[40:41]
	global_load_dword v40, v[40:41], off nt
.LBB0_319:
	s_or_b64 exec, exec, s[14:15]
	s_and_saveexec_b64 s[14:15], vcc
	s_cbranch_execz .LBB0_321
	v_or_b32_e32 v42, 34, v10
	v_ashrrev_i32_e32 v43, 31, v42
	v_lshlrev_b64 v[42:43], 11, v[42:43]
	v_lshl_add_u64 v[42:43], v[8:9], 0, v[42:43]
	global_load_dword v29, v[42:43], off nt
.LBB0_321:
	s_or_b64 exec, exec, s[14:15]
	v_mov_b32_e32 v41, 0
	v_mov_b32_e32 v42, 0
	s_and_saveexec_b64 s[14:15], vcc
	s_cbranch_execz .LBB0_323
	v_or_b32_e32 v42, 36, v10
	v_ashrrev_i32_e32 v43, 31, v42
	v_lshlrev_b64 v[42:43], 11, v[42:43]
	v_lshl_add_u64 v[42:43], v[8:9], 0, v[42:43]
	global_load_dword v42, v[42:43], off nt
.LBB0_323:
	s_or_b64 exec, exec, s[14:15]
	s_and_saveexec_b64 s[14:15], vcc
	s_cbranch_execz .LBB0_325
	v_or_b32_e32 v44, 38, v10
	v_ashrrev_i32_e32 v45, 31, v44
	v_lshlrev_b64 v[44:45], 11, v[44:45]
	v_lshl_add_u64 v[44:45], v[8:9], 0, v[44:45]
	global_load_dword v41, v[44:45], off nt
.LBB0_325:
	s_or_b64 exec, exec, s[14:15]
	v_mov_b32_e32 v43, 0
	v_mov_b32_e32 v44, 0
	s_and_saveexec_b64 s[14:15], vcc
	s_cbranch_execz .LBB0_327
	v_or_b32_e32 v44, 40, v10
	v_ashrrev_i32_e32 v45, 31, v44
	v_lshlrev_b64 v[44:45], 11, v[44:45]
	v_lshl_add_u64 v[44:45], v[8:9], 0, v[44:45]
	global_load_dword v44, v[44:45], off nt
.LBB0_327:
	s_or_b64 exec, exec, s[14:15]
	s_and_saveexec_b64 s[14:15], vcc
	s_cbranch_execz .LBB0_329
	v_or_b32_e32 v46, 42, v10
	v_ashrrev_i32_e32 v47, 31, v46
	v_lshlrev_b64 v[46:47], 11, v[46:47]
	v_lshl_add_u64 v[46:47], v[8:9], 0, v[46:47]
	global_load_dword v43, v[46:47], off nt
.LBB0_329:
	s_or_b64 exec, exec, s[14:15]
	v_mov_b32_e32 v45, 0
	v_mov_b32_e32 v46, 0
	s_and_saveexec_b64 s[14:15], vcc
	s_cbranch_execz .LBB0_331
	v_or_b32_e32 v46, 44, v10
	v_ashrrev_i32_e32 v47, 31, v46
	v_lshlrev_b64 v[46:47], 11, v[46:47]
	v_lshl_add_u64 v[46:47], v[8:9], 0, v[46:47]
	global_load_dword v46, v[46:47], off nt
.LBB0_331:
	s_or_b64 exec, exec, s[14:15]
	s_and_saveexec_b64 s[14:15], vcc
	s_cbranch_execz .LBB0_333
	v_or_b32_e32 v48, 46, v10
	v_ashrrev_i32_e32 v49, 31, v48
	v_lshlrev_b64 v[48:49], 11, v[48:49]
	v_lshl_add_u64 v[48:49], v[8:9], 0, v[48:49]
	global_load_dword v45, v[48:49], off nt
.LBB0_333:
	s_or_b64 exec, exec, s[14:15]
	v_mov_b32_e32 v47, 0
	v_mov_b32_e32 v48, 0
	s_and_saveexec_b64 s[14:15], vcc
	s_cbranch_execz .LBB0_335
	v_or_b32_e32 v48, 48, v10
	v_ashrrev_i32_e32 v49, 31, v48
	v_lshlrev_b64 v[48:49], 11, v[48:49]
	v_lshl_add_u64 v[48:49], v[8:9], 0, v[48:49]
	global_load_dword v48, v[48:49], off nt
.LBB0_335:
	s_or_b64 exec, exec, s[14:15]
	s_and_saveexec_b64 s[14:15], vcc
	s_cbranch_execz .LBB0_337
	v_or_b32_e32 v50, 50, v10
	v_ashrrev_i32_e32 v51, 31, v50
	v_lshlrev_b64 v[50:51], 11, v[50:51]
	v_lshl_add_u64 v[50:51], v[8:9], 0, v[50:51]
	global_load_dword v47, v[50:51], off nt
.LBB0_337:
	s_or_b64 exec, exec, s[14:15]
	v_mov_b32_e32 v49, 0
	v_mov_b32_e32 v50, 0
	s_and_saveexec_b64 s[14:15], vcc
	s_cbranch_execz .LBB0_339
	v_or_b32_e32 v50, 52, v10
	v_ashrrev_i32_e32 v51, 31, v50
	v_lshlrev_b64 v[50:51], 11, v[50:51]
	v_lshl_add_u64 v[50:51], v[8:9], 0, v[50:51]
	global_load_dword v50, v[50:51], off nt
.LBB0_339:
	s_or_b64 exec, exec, s[14:15]
	s_and_saveexec_b64 s[14:15], vcc
	s_cbranch_execz .LBB0_341
	v_or_b32_e32 v52, 54, v10
	v_ashrrev_i32_e32 v53, 31, v52
	v_lshlrev_b64 v[52:53], 11, v[52:53]
	v_lshl_add_u64 v[52:53], v[8:9], 0, v[52:53]
	global_load_dword v49, v[52:53], off nt
.LBB0_341:
	s_or_b64 exec, exec, s[14:15]
	v_mov_b32_e32 v51, 0
	v_mov_b32_e32 v52, 0
	s_and_saveexec_b64 s[14:15], vcc
	s_cbranch_execz .LBB0_343
	v_or_b32_e32 v52, 56, v10
	v_ashrrev_i32_e32 v53, 31, v52
	v_lshlrev_b64 v[52:53], 11, v[52:53]
	v_lshl_add_u64 v[52:53], v[8:9], 0, v[52:53]
	global_load_dword v52, v[52:53], off nt
.LBB0_343:
	s_or_b64 exec, exec, s[14:15]
	s_and_saveexec_b64 s[14:15], vcc
	s_cbranch_execz .LBB0_345
	v_or_b32_e32 v54, 58, v10
	v_ashrrev_i32_e32 v55, 31, v54
	v_lshlrev_b64 v[54:55], 11, v[54:55]
	v_lshl_add_u64 v[54:55], v[8:9], 0, v[54:55]
	global_load_dword v51, v[54:55], off nt
.LBB0_345:
	s_or_b64 exec, exec, s[14:15]
	v_mov_b32_e32 v53, 0
	v_mov_b32_e32 v54, 0
	s_and_saveexec_b64 s[14:15], vcc
	s_cbranch_execz .LBB0_347
	v_or_b32_e32 v54, 60, v10
	v_ashrrev_i32_e32 v55, 31, v54
	v_lshlrev_b64 v[54:55], 11, v[54:55]
	v_lshl_add_u64 v[54:55], v[8:9], 0, v[54:55]
	global_load_dword v54, v[54:55], off nt
.LBB0_347:
	s_or_b64 exec, exec, s[14:15]
	s_and_saveexec_b64 s[14:15], vcc
	s_cbranch_execz .LBB0_284
	v_or_b32_e32 v56, 62, v10
	v_ashrrev_i32_e32 v57, 31, v56
	v_lshlrev_b64 v[56:57], 11, v[56:57]
	v_lshl_add_u64 v[8:9], v[8:9], 0, v[56:57]
	global_load_dword v53, v[8:9], off nt
	s_branch .LBB0_284

; __device__ __forceinline__ void conv_weight(const float* W, int ldw, int K, int Nphys, int Nvalid, int mode, const float* g, bf16_t* WT, LAS float* scr, int gw, int NGW, int lane, int& rot) {
;     ...
;     for (int it = g0; it < items; it += NGW) {
;         const int kb = it / nblk, nb = it % nblk, k0 = 64 * kb, n0 = 32 * nb;
;         const int prow = n0 + (lane & 31); const bool ok = prow < Nvalid; const int col = ok ? colmap(mode, prow) : 0;
;         float wv_[32];
; #pragma unroll
;         for (int i = 0; i < 32; ++i) { const int kk = 2 * i + (lane >> 5); wv_[i] = ok ? W[(size_t)(k0 + kk) * ldw + col] : 0.f; }
.LBB0_352:
	s_ashr_i32 s12, s0, 31
	s_lshr_b32 s12, s12, 27
	s_add_i32 s12, s0, s12
	s_ashr_i32 s13, s12, 5
	s_lshl_b32 s12, s13, 6
	s_lshl_b32 s13, s13, 10
	s_sub_i32 s14, s17, s13
	v_add_u32_e32 v5, s14, v30
	v_cmp_gt_i32_e32 vcc, s1, v5
	v_or_b32_e32 v10, s12, v4
	v_mov_b32_e32 v13, 0
	v_cndmask_b32_e32 v8, 0, v5, vcc
	v_ashrrev_i32_e32 v9, 31, v8
	v_lshl_add_u64 v[8:9], v[8:9], 2, s[10:11]
	v_mov_b32_e32 v5, 0
	s_and_saveexec_b64 s[14:15], vcc
	s_cbranch_execz .LBB0_354
	v_ashrrev_i32_e32 v11, 31, v10
	v_lshlrev_b64 v[14:15], 12, v[10:11]
	v_lshl_add_u64 v[14:15], v[8:9], 0, v[14:15]
	global_load_dword v5, v[14:15], off nt
.LBB0_354:
	s_or_b64 exec, exec, s[14:15]
	s_and_saveexec_b64 s[14:15], vcc
	s_cbranch_execz .LBB0_356
	v_or_b32_e32 v14, 2, v10
	v_ashrrev_i32_e32 v15, 31, v14
	v_lshlrev_b64 v[14:15], 12, v[14:15]
	v_lshl_add_u64 v[14:15], v[8:9], 0, v[14:15]
	global_load_dword v13, v[14:15], off nt
.LBB0_356:
	s_or_b64 exec, exec, s[14:15]
	v_mov_b32_e32 v11, 0
	v_mov_b32_e32 v14, 0
	s_and_saveexec_b64 s[14:15], vcc
	s_cbranch_execz .LBB0_358
	v_or_b32_e32 v14, 4, v10
	v_ashrrev_i32_e32 v15, 31, v14
	v_lshlrev_b64 v[14:15], 12, v[14:15]
	v_lshl_add_u64 v[14:15], v[8:9], 0, v[14:15]
	global_load_dword v14, v[14:15], off nt
.LBB0_358:
	s_or_b64 exec, exec, s[14:15]
	s_and_saveexec_b64 s[14:15], vcc
	s_cbranch_execz .LBB0_360
	v_or_b32_e32 v16, 6, v10
	v_ashrrev_i32_e32 v17, 31, v16
	v_lshlrev_b64 v[16:17], 12, v[16:17]
	v_lshl_add_u64 v[16:17], v[8:9], 0, v[16:17]
	global_load_dword v11, v[16:17], off nt
.LBB0_360:
	s_or_b64 exec, exec, s[14:15]
	v_mov_b32_e32 v15, 0
	v_mov_b32_e32 v16, 0
	s_and_saveexec_b64 s[14:15], vcc
	s_cbranch_execz .LBB0_362
	v_or_b32_e32 v16, 8, v10
	v_ashrrev_i32_e32 v17, 31, v16
	v_lshlrev_b64 v[16:17], 12, v[16:17]
	v_lshl_add_u64 v[16:17], v[8:9], 0, v[16:17]
	global_load_dword v16, v[16:17], off nt
.LBB0_362:
	s_or_b64 exec, exec, s[14:15]
	s_and_saveexec_b64 s[14:15], vcc
	s_cbranch_execz .LBB0_364
	v_or_b32_e32 v20, 10, v10
	v_ashrrev_i32_e32 v21, 31, v20
	v_lshlrev_b64 v[20:21], 12, v[20:21]
	v_lshl_add_u64 v[20:21], v[8:9], 0, v[20:21]
	global_load_dword v15, v[20:21], off nt
.LBB0_364:
	s_or_b64 exec, exec, s[14:15]
	v_mov_b32_e32 v17, 0
	v_mov_b32_e32 v20, 0
	s_and_saveexec_b64 s[14:15], vcc
	s_cbranch_execz .LBB0_366
	v_or_b32_e32 v20, 12, v10
	v_ashrrev_i32_e32 v21, 31, v20
	v_lshlrev_b64 v[20:21], 12, v[20:21]
	v_lshl_add_u64 v[20:21], v[8:9], 0, v[20:21]
	global_load_dword v20, v[20:21], off nt
.LBB0_366:
	s_or_b64 exec, exec, s[14:15]
	s_and_saveexec_b64 s[14:15], vcc
	s_cbranch_execz .LBB0_368
	v_or_b32_e32 v22, 14, v10
	v_ashrrev_i32_e32 v23, 31, v22
	v_lshlrev_b64 v[22:23], 12, v[22:23]
	v_lshl_add_u64 v[22:23], v[8:9], 0, v[22:23]
	global_load_dword v17, v[22:23], off nt
.LBB0_368:
	s_or_b64 exec, exec, s[14:15]
	v_mov_b32_e32 v21, 0
	v_mov_b32_e32 v22, 0
	s_and_saveexec_b64 s[14:15], vcc
	s_cbranch_execz .LBB0_370
	v_or_b32_e32 v22, 16, v10
	v_ashrrev_i32_e32 v23, 31, v22
	v_lshlrev_b64 v[22:23], 12, v[22:23]
	v_lshl_add_u64 v[22:23], v[8:9], 0, v[22:23]
	global_load_dword v22, v[22:23], off nt
.LBB0_370:
	s_or_b64 exec, exec, s[14:15]
	s_and_saveexec_b64 s[14:15], vcc
	s_cbranch_execz .LBB0_372
	v_or_b32_e32 v24, 18, v10
	v_ashrrev_i32_e32 v25, 31, v24
	v_lshlrev_b64 v[24:25], 12, v[24:25]
	v_lshl_add_u64 v[24:25], v[8:9], 0, v[24:25]
	global_load_dword v21, v[24:25], off nt
.LBB0_372:
	s_or_b64 exec, exec, s[14:15]
	v_mov_b32_e32 v23, 0
	v_mov_b32_e32 v24, 0
	s_and_saveexec_b64 s[14:15], vcc
	s_cbranch_execz .LBB0_374
	v_or_b32_e32 v24, 20, v10
	v_ashrrev_i32_e32 v25, 31, v24
	v_lshlrev_b64 v[24:25], 12, v[24:25]
	v_lshl_add_u64 v[24:25], v[8:9], 0, v[24:25]
	global_load_dword v24, v[24:25], off nt
.LBB0_374:
	s_or_b64 exec, exec, s[14:15]
	s_and_saveexec_b64 s[14:15], vcc
	s_cbranch_execz .LBB0_376
	v_or_b32_e32 v26, 22, v10
	v_ashrrev_i32_e32 v27, 31, v26
	v_lshlrev_b64 v[26:27], 12, v[26:27]
	v_lshl_add_u64 v[26:27], v[8:9], 0, v[26:27]
	global_load_dword v23, v[26:27], off nt
.LBB0_376:
	s_or_b64 exec, exec, s[14:15]
	v_mov_b32_e32 v25, 0
	v_mov_b32_e32 v26, 0
	s_and_saveexec_b64 s[14:15], vcc
	s_cbranch_execz .LBB0_378
	v_or_b32_e32 v26, 24, v10
	v_ashrrev_i32_e32 v27, 31, v26
	v_lshlrev_b64 v[26:27], 12, v[26:27]
	v_lshl_add_u64 v[26:27], v[8:9], 0, v[26:27]
	global_load_dword v26, v[26:27], off nt
.LBB0_378:
	s_or_b64 exec, exec, s[14:15]
	s_and_saveexec_b64 s[14:15], vcc
	s_cbranch_execz .LBB0_380
	v_or_b32_e32 v28, 26, v10
	v_ashrrev_i32_e32 v29, 31, v28
	v_lshlrev_b64 v[28:29], 12, v[28:29]
	v_lshl_add_u64 v[28:29], v[8:9], 0, v[28:29]
	global_load_dword v25, v[28:29], off nt
.LBB0_380:
	s_or_b64 exec, exec, s[14:15]
	v_mov_b32_e32 v27, 0
	v_mov_b32_e32 v28, 0
	s_and_saveexec_b64 s[14:15], vcc
	s_cbranch_execz .LBB0_382
	v_or_b32_e32 v28, 28, v10
	v_ashrrev_i32_e32 v29, 31, v28
	v_lshlrev_b64 v[28:29], 12, v[28:29]
	v_lshl_add_u64 v[28:29], v[8:9], 0, v[28:29]
	global_load_dword v28, v[28:29], off nt
.LBB0_382:
	s_or_b64 exec, exec, s[14:15]
	s_and_saveexec_b64 s[14:15], vcc
	s_cbranch_execz .LBB0_384
	v_or_b32_e32 v40, 30, v10
	v_ashrrev_i32_e32 v41, 31, v40
	v_lshlrev_b64 v[40:41], 12, v[40:41]
	v_lshl_add_u64 v[40:41], v[8:9], 0, v[40:41]
	global_load_dword v27, v[40:41], off nt
; __device__ __forceinline__ void conv_weight(const float* W, int ldw, int K, int Nphys, int Nvalid, int mode, const float* g, bf16_t* WT, LAS float* scr, int gw, int NGW, int lane, int& rot) {
;     ...
;         for (int i = 0; i < 32; ++i) { const int kk = 2 * i + (lane >> 5); wv_[i] = ok ? W[(size_t)(k0 + kk) * ldw + col] : 0.f; }
.LBB0_384:
	s_or_b64 exec, exec, s[14:15]
	v_mov_b32_e32 v29, 0
	v_mov_b32_e32 v40, 0
	s_and_saveexec_b64 s[14:15], vcc
	s_cbranch_execz .LBB0_386
	v_or_b32_e32 v40, 32, v10
	v_ashrrev_i32_e32 v41, 31, v40
	v_lshlrev_b64 v[40:41], 12, v[40:41]
	v_lshl_add_u64 v[40:41], v[8:9], 0, v[40:41]
	global_load_dword v40, v[40:41], off nt
.LBB0_386:
	s_or_b64 exec, exec, s[14:15]
	s_and_saveexec_b64 s[14:15], vcc
	s_cbranch_execz .LBB0_388
	v_or_b32_e32 v42, 34, v10
	v_ashrrev_i32_e32 v43, 31, v42
	v_lshlrev_b64 v[42:43], 12, v[42:43]
	v_lshl_add_u64 v[42:43], v[8:9], 0, v[42:43]
	global_load_dword v29, v[42:43], off nt
.LBB0_388:
	s_or_b64 exec, exec, s[14:15]
	v_mov_b32_e32 v41, 0
	v_mov_b32_e32 v42, 0
	s_and_saveexec_b64 s[14:15], vcc
	s_cbranch_execz .LBB0_390
	v_or_b32_e32 v42, 36, v10
	v_ashrrev_i32_e32 v43, 31, v42
	v_lshlrev_b64 v[42:43], 12, v[42:43]
	v_lshl_add_u64 v[42:43], v[8:9], 0, v[42:43]
	global_load_dword v42, v[42:43], off nt
.LBB0_390:
	s_or_b64 exec, exec, s[14:15]
	s_and_saveexec_b64 s[14:15], vcc
	s_cbranch_execz .LBB0_392
	v_or_b32_e32 v44, 38, v10
	v_ashrrev_i32_e32 v45, 31, v44
	v_lshlrev_b64 v[44:45], 12, v[44:45]
	v_lshl_add_u64 v[44:45], v[8:9], 0, v[44:45]
	global_load_dword v41, v[44:45], off nt
.LBB0_392:
	s_or_b64 exec, exec, s[14:15]
	v_mov_b32_e32 v43, 0
	v_mov_b32_e32 v44, 0
	s_and_saveexec_b64 s[14:15], vcc
	s_cbranch_execz .LBB0_394
	v_or_b32_e32 v44, 40, v10
	v_ashrrev_i32_e32 v45, 31, v44
	v_lshlrev_b64 v[44:45], 12, v[44:45]
	v_lshl_add_u64 v[44:45], v[8:9], 0, v[44:45]
	global_load_dword v44, v[44:45], off nt
.LBB0_394:
	s_or_b64 exec, exec, s[14:15]
	s_and_saveexec_b64 s[14:15], vcc
	s_cbranch_execz .LBB0_396
	v_or_b32_e32 v46, 42, v10
	v_ashrrev_i32_e32 v47, 31, v46
	v_lshlrev_b64 v[46:47], 12, v[46:47]
	v_lshl_add_u64 v[46:47], v[8:9], 0, v[46:47]
	global_load_dword v43, v[46:47], off nt
.LBB0_396:
	s_or_b64 exec, exec, s[14:15]
	v_mov_b32_e32 v45, 0
	v_mov_b32_e32 v46, 0
	s_and_saveexec_b64 s[14:15], vcc
	s_cbranch_execz .LBB0_398
	v_or_b32_e32 v46, 44, v10
	v_ashrrev_i32_e32 v47, 31, v46
	v_lshlrev_b64 v[46:47], 12, v[46:47]
	v_lshl_add_u64 v[46:47], v[8:9], 0, v[46:47]
	global_load_dword v46, v[46:47], off nt
.LBB0_398:
	s_or_b64 exec, exec, s[14:15]
	s_and_saveexec_b64 s[14:15], vcc
	s_cbranch_execz .LBB0_400
	v_or_b32_e32 v48, 46, v10
	v_ashrrev_i32_e32 v49, 31, v48
	v_lshlrev_b64 v[48:49], 12, v[48:49]
	v_lshl_add_u64 v[48:49], v[8:9], 0, v[48:49]
	global_load_dword v45, v[48:49], off nt
.LBB0_400:
	s_or_b64 exec, exec, s[14:15]
	v_mov_b32_e32 v47, 0
	v_mov_b32_e32 v48, 0
	s_and_saveexec_b64 s[14:15], vcc
	s_cbranch_execz .LBB0_402
	v_or_b32_e32 v48, 48, v10
	v_ashrrev_i32_e32 v49, 31, v48
	v_lshlrev_b64 v[48:49], 12, v[48:49]
	v_lshl_add_u64 v[48:49], v[8:9], 0, v[48:49]
	global_load_dword v48, v[48:49], off nt
.LBB0_402:
	s_or_b64 exec, exec, s[14:15]
	s_and_saveexec_b64 s[14:15], vcc
	s_cbranch_execz .LBB0_404
	v_or_b32_e32 v50, 50, v10
	v_ashrrev_i32_e32 v51, 31, v50
	v_lshlrev_b64 v[50:51], 12, v[50:51]
	v_lshl_add_u64 v[50:51], v[8:9], 0, v[50:51]
	global_load_dword v47, v[50:51], off nt
.LBB0_404:
	s_or_b64 exec, exec, s[14:15]
	v_mov_b32_e32 v49, 0
	v_mov_b32_e32 v50, 0
	s_and_saveexec_b64 s[14:15], vcc
	s_cbranch_execz .LBB0_406
	v_or_b32_e32 v50, 52, v10
	v_ashrrev_i32_e32 v51, 31, v50
	v_lshlrev_b64 v[50:51], 12, v[50:51]
	v_lshl_add_u64 v[50:51], v[8:9], 0, v[50:51]
	global_load_dword v50, v[50:51], off nt
.LBB0_406:
	s_or_b64 exec, exec, s[14:15]
	s_and_saveexec_b64 s[14:15], vcc
	s_cbranch_execz .LBB0_408
	v_or_b32_e32 v52, 54, v10
	v_ashrrev_i32_e32 v53, 31, v52
	v_lshlrev_b64 v[52:53], 12, v[52:53]
	v_lshl_add_u64 v[52:53], v[8:9], 0, v[52:53]
	global_load_dword v49, v[52:53], off nt
.LBB0_408:
	s_or_b64 exec, exec, s[14:15]
	v_mov_b32_e32 v51, 0
	v_mov_b32_e32 v52, 0
	s_and_saveexec_b64 s[14:15], vcc
	s_cbranch_execz .LBB0_410
	v_or_b32_e32 v52, 56, v10
	v_ashrrev_i32_e32 v53, 31, v52
	v_lshlrev_b64 v[52:53], 12, v[52:53]
	v_lshl_add_u64 v[52:53], v[8:9], 0, v[52:53]
	global_load_dword v52, v[52:53], off nt
.LBB0_410:
	s_or_b64 exec, exec, s[14:15]
	s_and_saveexec_b64 s[14:15], vcc
	s_cbranch_execz .LBB0_412
	v_or_b32_e32 v54, 58, v10
	v_ashrrev_i32_e32 v55, 31, v54
	v_lshlrev_b64 v[54:55], 12, v[54:55]
	v_lshl_add_u64 v[54:55], v[8:9], 0, v[54:55]
	global_load_dword v51, v[54:55], off nt
.LBB0_412:
	s_or_b64 exec, exec, s[14:15]
	v_mov_b32_e32 v53, 0
	v_mov_b32_e32 v54, 0
	s_and_saveexec_b64 s[14:15], vcc
	s_cbranch_execz .LBB0_414
	v_or_b32_e32 v54, 60, v10
	v_ashrrev_i32_e32 v55, 31, v54
	v_lshlrev_b64 v[54:55], 12, v[54:55]
	v_lshl_add_u64 v[54:55], v[8:9], 0, v[54:55]
	global_load_dword v54, v[54:55], off nt
.LBB0_414:
	s_or_b64 exec, exec, s[14:15]
	s_and_saveexec_b64 s[14:15], vcc
	s_cbranch_execz .LBB0_351
	v_or_b32_e32 v56, 62, v10
	v_ashrrev_i32_e32 v57, 31, v56
	v_lshlrev_b64 v[56:57], 12, v[56:57]
	v_lshl_add_u64 v[8:9], v[8:9], 0, v[56:57]
	global_load_dword v53, v[8:9], off nt
	s_branch .LBB0_351

; #define LAS __attribute__((address_space(3)))
; __device__ __forceinline__ int colmap(int mode, int p) {
;     if (mode == 1) { if ((p >= 512 && p < 1024) || (p >= 1536 && p < 2048)) { const int w = p & 63; return (p & ~63) + 32 * ((w >> 4) & 1) + 16 * (w >> 5) + (w & 15); } return p; }
;     if (mode == 2) return ((p >> 7) & 1) * 2816 + (p >> 8) * 128 + (p & 127);
;     return p;
; }
; __device__ __forceinline__ void conv_weight(const float* W, int ldw, int K, int Nphys, int Nvalid, int mode, const float* g, bf16_t* WT, LAS float* scr, int gw, int NGW, int lane, int& rot) {
;     const int nblk = Nphys / 32, items = (K / 64) * nblk;
;     const int g0 = (gw - rot % NGW + NGW) % NGW; rot += items;
;     for (int it = g0; it < items; it += NGW) {
;         const int kb = it / nblk, nb = it % nblk, k0 = 64 * kb, n0 = 32 * nb;
;         const int prow = n0 + (lane & 31); const bool ok = prow < Nvalid; const int col = ok ? colmap(mode, prow) : 0;
;         float wv_[32];
; #pragma unroll
;         for (int i = 0; i < 32; ++i) { const int kk = 2 * i + (lane >> 5); wv_[i] = ok ? W[(size_t)(k0 + kk) * ldw + col] : 0.f; }
.LBB0_420:
	s_mul_hi_i32 s4, s0, 0x2e8ba2e9
	s_lshr_b32 s5, s4, 31
	s_ashr_i32 s16, s4, 5
	s_add_i32 s16, s16, s5
	s_mul_i32 s27, s16, 0xffffea00
	s_add_i32 s27, s27, s1
	v_add_u32_e32 v10, s27, v30
	v_cmp_gt_i32_e32 vcc, s23, v10
	v_mov_b64_e32 v[8:9], 0
	s_and_saveexec_b64 s[4:5], vcc
	s_mul_i32 s18, s16, 0xfffff500
	s_bfe_i32 s17, s0, 0x10002
	s_add_i32 s18, s21, s18
	s_and_b32 s17, s17, 0xb00
	s_and_b32 s18, s18, 0xffffff80
	s_add_i32 s17, s17, s18
	v_and_b32_e32 v8, 0x7f, v10
	v_or_b32_e32 v8, s17, v8
	v_ashrrev_i32_e32 v9, 31, v8
	s_or_b64 exec, exec, s[4:5]
	s_lshl_b32 s16, s16, 6
	v_lshl_add_u64 v[28:29], v[8:9], 2, s[12:13]
	v_or_b32_e32 v26, s16, v4
	v_mov_b32_e32 v85, 0
	v_mov_b32_e32 v86, 0
	s_and_saveexec_b64 s[4:5], vcc
	s_cbranch_execz .LBB0_424
	v_mad_i64_i32 v[8:9], s[18:19], v26, s24, v[28:29]
	global_load_dword v86, v[8:9], off nt
.LBB0_424:
	s_or_b64 exec, exec, s[4:5]
	s_and_saveexec_b64 s[4:5], vcc
	s_cbranch_execz .LBB0_426
	v_or_b32_e32 v8, 2, v26
	v_mad_i64_i32 v[8:9], s[18:19], v8, s24, v[28:29]
	global_load_dword v85, v[8:9], off nt
.LBB0_426:
	s_or_b64 exec, exec, s[4:5]
	v_mov_b32_e32 v25, 0
	v_mov_b32_e32 v24, 0
	s_and_saveexec_b64 s[4:5], vcc
	s_cbranch_execz .LBB0_428
	v_or_b32_e32 v8, 4, v26
	v_mad_i64_i32 v[8:9], s[18:19], v8, s24, v[28:29]
	global_load_dword v24, v[8:9], off nt
.LBB0_428:
	s_or_b64 exec, exec, s[4:5]
	s_and_saveexec_b64 s[4:5], vcc
	s_cbranch_execz .LBB0_430
	v_or_b32_e32 v8, 6, v26
	v_mad_i64_i32 v[8:9], s[18:19], v8, s24, v[28:29]
	global_load_dword v25, v[8:9], off nt
.LBB0_430:
	s_or_b64 exec, exec, s[4:5]
	v_mov_b32_e32 v82, 0
	v_mov_b32_e32 v84, 0
	s_and_saveexec_b64 s[4:5], vcc
	s_cbranch_execz .LBB0_432
	v_or_b32_e32 v8, 8, v26
	v_mad_i64_i32 v[8:9], s[18:19], v8, s24, v[28:29]
	global_load_dword v84, v[8:9], off nt
.LBB0_432:
	s_or_b64 exec, exec, s[4:5]
	s_and_saveexec_b64 s[4:5], vcc
	s_cbranch_execz .LBB0_434
	v_or_b32_e32 v8, 10, v26
	v_mad_i64_i32 v[8:9], s[18:19], v8, s24, v[28:29]
	global_load_dword v82, v[8:9], off nt
.LBB0_434:
	s_or_b64 exec, exec, s[4:5]
	v_mov_b32_e32 v23, 0
	v_mov_b32_e32 v22, 0
	s_and_saveexec_b64 s[4:5], vcc
	s_cbranch_execz .LBB0_436
	v_or_b32_e32 v8, 12, v26
	v_mad_i64_i32 v[8:9], s[18:19], v8, s24, v[28:29]
	global_load_dword v22, v[8:9], off nt
.LBB0_436:
	s_or_b64 exec, exec, s[4:5]
	s_and_saveexec_b64 s[4:5], vcc
	s_cbranch_execz .LBB0_438
	v_or_b32_e32 v8, 14, v26
	v_mad_i64_i32 v[8:9], s[18:19], v8, s24, v[28:29]
	global_load_dword v23, v[8:9], off nt
.LBB0_438:
	s_or_b64 exec, exec, s[4:5]
	v_mov_b32_e32 v80, 0
	v_mov_b32_e32 v83, 0
	s_and_saveexec_b64 s[4:5], vcc
	s_cbranch_execz .LBB0_440
	v_or_b32_e32 v8, 16, v26
	v_mad_i64_i32 v[8:9], s[18:19], v8, s24, v[28:29]
	global_load_dword v83, v[8:9], off nt
.LBB0_440:
	s_or_b64 exec, exec, s[4:5]
	s_and_saveexec_b64 s[4:5], vcc
	s_cbranch_execz .LBB0_442
	v_or_b32_e32 v8, 18, v26
	v_mad_i64_i32 v[8:9], s[18:19], v8, s24, v[28:29]
	global_load_dword v80, v[8:9], off nt
.LBB0_442:
	s_or_b64 exec, exec, s[4:5]
	v_mov_b32_e32 v21, 0
	v_mov_b32_e32 v20, 0
	s_and_saveexec_b64 s[4:5], vcc
	s_cbranch_execz .LBB0_444
	v_or_b32_e32 v8, 20, v26
	v_mad_i64_i32 v[8:9], s[18:19], v8, s24, v[28:29]
	global_load_dword v20, v[8:9], off nt
.LBB0_444:
	s_or_b64 exec, exec, s[4:5]
	s_and_saveexec_b64 s[4:5], vcc
	s_cbranch_execz .LBB0_446
	v_or_b32_e32 v8, 22, v26
	v_mad_i64_i32 v[8:9], s[18:19], v8, s24, v[28:29]
	global_load_dword v21, v[8:9], off nt
.LBB0_446:
	s_or_b64 exec, exec, s[4:5]
	v_mov_b32_e32 v78, 0
	v_mov_b32_e32 v81, 0
	s_and_saveexec_b64 s[4:5], vcc
	s_cbranch_execz .LBB0_448
	v_or_b32_e32 v8, 24, v26
	v_mad_i64_i32 v[8:9], s[18:19], v8, s24, v[28:29]
	global_load_dword v81, v[8:9], off nt
.LBB0_448:
	s_or_b64 exec, exec, s[4:5]
	s_and_saveexec_b64 s[4:5], vcc
	s_cbranch_execz .LBB0_450
	v_or_b32_e32 v8, 26, v26
	v_mad_i64_i32 v[8:9], s[18:19], v8, s24, v[28:29]
	global_load_dword v78, v[8:9], off nt
.LBB0_450:
	s_or_b64 exec, exec, s[4:5]
	v_mov_b32_e32 v17, 0
	v_mov_b32_e32 v16, 0
	s_and_saveexec_b64 s[4:5], vcc
	s_cbranch_execz .LBB0_452
	v_or_b32_e32 v8, 28, v26
	v_mad_i64_i32 v[8:9], s[18:19], v8, s24, v[28:29]
	global_load_dword v16, v[8:9], off nt
.LBB0_452:
	s_or_b64 exec, exec, s[4:5]
	s_and_saveexec_b64 s[4:5], vcc
	s_cbranch_execz .LBB0_454
	v_or_b32_e32 v8, 30, v26
	v_mad_i64_i32 v[8:9], s[18:19], v8, s24, v[28:29]
	global_load_dword v17, v[8:9], off nt
; __device__ __forceinline__ void conv_weight(const float* W, int ldw, int K, int Nphys, int Nvalid, int mode, const float* g, bf16_t* WT, LAS float* scr, int gw, int NGW, int lane, int& rot) {
;     ...
;         for (int i = 0; i < 32; ++i) { const int kk = 2 * i + (lane >> 5); wv_[i] = ok ? W[(size_t)(k0 + kk) * ldw + col] : 0.f; }
; #pragma unroll
;         for (int i = 0; i < 32; ++i) { const int kk = 2 * i + (lane >> 5); float v = wv_[i]; if (g) v *= g[k0 + kk]; scr[kk * 33 + (lane & 31)] = v; }
.LBB0_454:
	s_or_b64 exec, exec, s[4:5]
	v_mov_b32_e32 v76, 0
	v_mov_b32_e32 v79, 0
	s_and_saveexec_b64 s[4:5], vcc
	s_cbranch_execz .LBB0_456
	v_or_b32_e32 v8, 32, v26
	v_mad_i64_i32 v[8:9], s[18:19], v8, s24, v[28:29]
	global_load_dword v79, v[8:9], off nt
.LBB0_456:
	s_or_b64 exec, exec, s[4:5]
	s_and_saveexec_b64 s[4:5], vcc
	s_cbranch_execz .LBB0_458
	v_or_b32_e32 v8, 34, v26
	v_mad_i64_i32 v[8:9], s[18:19], v8, s24, v[28:29]
	global_load_dword v76, v[8:9], off nt
.LBB0_458:
	s_or_b64 exec, exec, s[4:5]
	v_mov_b32_e32 v15, 0
	v_mov_b32_e32 v14, 0
	s_and_saveexec_b64 s[4:5], vcc
	s_cbranch_execz .LBB0_460
	v_or_b32_e32 v8, 36, v26
	v_mad_i64_i32 v[8:9], s[18:19], v8, s24, v[28:29]
	global_load_dword v14, v[8:9], off nt
.LBB0_460:
	s_or_b64 exec, exec, s[4:5]
	s_and_saveexec_b64 s[4:5], vcc
	s_cbranch_execz .LBB0_462
	v_or_b32_e32 v8, 38, v26
	v_mad_i64_i32 v[8:9], s[18:19], v8, s24, v[28:29]
	global_load_dword v15, v[8:9], off nt
.LBB0_462:
	s_or_b64 exec, exec, s[4:5]
	v_mov_b32_e32 v74, 0
	v_mov_b32_e32 v77, 0
	s_and_saveexec_b64 s[4:5], vcc
	s_cbranch_execz .LBB0_464
	v_or_b32_e32 v8, 40, v26
	v_mad_i64_i32 v[8:9], s[18:19], v8, s24, v[28:29]
	global_load_dword v77, v[8:9], off nt
.LBB0_464:
	s_or_b64 exec, exec, s[4:5]
	s_and_saveexec_b64 s[4:5], vcc
	s_cbranch_execz .LBB0_466
	v_or_b32_e32 v8, 42, v26
	v_mad_i64_i32 v[8:9], s[18:19], v8, s24, v[28:29]
	global_load_dword v74, v[8:9], off nt
.LBB0_466:
	s_or_b64 exec, exec, s[4:5]
	v_mov_b32_e32 v13, 0
	v_mov_b32_e32 v12, 0
	s_and_saveexec_b64 s[4:5], vcc
	s_cbranch_execz .LBB0_468
	v_or_b32_e32 v8, 44, v26
	v_mad_i64_i32 v[8:9], s[18:19], v8, s24, v[28:29]
	global_load_dword v12, v[8:9], off nt
.LBB0_468:
	s_or_b64 exec, exec, s[4:5]
	s_and_saveexec_b64 s[4:5], vcc
	s_cbranch_execz .LBB0_470
	v_or_b32_e32 v8, 46, v26
	v_mad_i64_i32 v[8:9], s[18:19], v8, s24, v[28:29]
	global_load_dword v13, v[8:9], off nt
.LBB0_470:
	s_or_b64 exec, exec, s[4:5]
	v_mov_b32_e32 v73, 0
	v_mov_b32_e32 v75, 0
	s_and_saveexec_b64 s[4:5], vcc
	s_cbranch_execz .LBB0_472
	v_or_b32_e32 v8, 48, v26
	v_mad_i64_i32 v[8:9], s[18:19], v8, s24, v[28:29]
	global_load_dword v75, v[8:9], off nt
.LBB0_472:
	s_or_b64 exec, exec, s[4:5]
	s_and_saveexec_b64 s[4:5], vcc
	s_cbranch_execz .LBB0_474
	v_or_b32_e32 v8, 50, v26
	v_mad_i64_i32 v[8:9], s[18:19], v8, s24, v[28:29]
	global_load_dword v73, v[8:9], off nt
.LBB0_474:
	s_or_b64 exec, exec, s[4:5]
	v_mov_b32_e32 v11, 0
	v_mov_b32_e32 v10, 0
	s_and_saveexec_b64 s[4:5], vcc
	s_cbranch_execz .LBB0_476
	v_or_b32_e32 v8, 52, v26
	v_mad_i64_i32 v[8:9], s[18:19], v8, s24, v[28:29]
	global_load_dword v10, v[8:9], off nt
.LBB0_476:
	s_or_b64 exec, exec, s[4:5]
	s_and_saveexec_b64 s[4:5], vcc
	s_cbranch_execz .LBB0_478
	v_or_b32_e32 v8, 54, v26
	v_mad_i64_i32 v[8:9], s[18:19], v8, s24, v[28:29]
	global_load_dword v11, v[8:9], off nt
.LBB0_478:
	s_or_b64 exec, exec, s[4:5]
	v_mov_b32_e32 v71, 0
	v_mov_b32_e32 v72, 0
	s_and_saveexec_b64 s[4:5], vcc
	s_cbranch_execz .LBB0_480
	v_or_b32_e32 v8, 56, v26
	v_mad_i64_i32 v[8:9], s[18:19], v8, s24, v[28:29]
	global_load_dword v72, v[8:9], off nt
.LBB0_480:
	s_or_b64 exec, exec, s[4:5]
	s_and_saveexec_b64 s[4:5], vcc
	s_cbranch_execz .LBB0_482
	v_or_b32_e32 v8, 58, v26
	v_mad_i64_i32 v[8:9], s[18:19], v8, s24, v[28:29]
	global_load_dword v71, v[8:9], off nt
.LBB0_482:
	s_or_b64 exec, exec, s[4:5]
	v_mov_b32_e32 v9, 0
	v_mov_b32_e32 v8, 0
	s_and_saveexec_b64 s[4:5], vcc
	s_cbranch_execz .LBB0_484
	v_or_b32_e32 v8, 60, v26
	v_mad_i64_i32 v[88:89], s[18:19], v8, s24, v[28:29]
	global_load_dword v8, v[88:89], off nt
.LBB0_484:
	s_or_b64 exec, exec, s[4:5]
	s_and_saveexec_b64 s[4:5], vcc
	s_cbranch_execz .LBB0_486
	v_or_b32_e32 v9, 62, v26
	v_mad_i64_i32 v[28:29], s[18:19], v9, s24, v[28:29]
	global_load_dword v9, v[28:29], off nt
.LBB0_486:
	s_or_b64 exec, exec, s[4:5]
	v_cndmask_b32_e64 v27, 0, 1, s[14:15]
	v_cmp_ne_u32_e64 s[4:5], 1, v27
	s_andn2_b64 vcc, exec, s[14:15]
	s_cbranch_vccnz .LBB0_509
	v_ashrrev_i32_e32 v27, 31, v26
	s_ashr_i32 s17, s16, 31
	v_lshl_add_u64 v[26:27], v[26:27], 2, s[10:11]
	v_lshl_add_u64 v[28:29], s[16:17], 0, v[4:5]
	v_lshl_add_u64 v[28:29], v[28:29], 2, s[10:11]
	global_load_dword v87, v[26:27], off nt
	global_load_dword v90, v[28:29], off offset:8
	global_load_dword v88, v[28:29], off offset:16
	global_load_dword v89, v[28:29], off offset:24
	s_waitcnt vmcnt(3)
	v_mul_f32_e32 v26, v86, v87
	s_waitcnt vmcnt(2)
	v_mul_f32_e32 v28, v85, v90
	ds_write_b32 v35, v26
	s_waitcnt vmcnt(0)
	v_pk_mul_f32 v[26:27], v[24:25], v[88:89]
	ds_write_b32 v56, v28
	s_cbranch_execnz .LBB0_489

; __device__ __forceinline__ void conv_weight(const float* W, int ldw, int K, int Nphys, int Nvalid, int mode, const float* g, bf16_t* WT, LAS float* scr, int gw, int NGW, int lane, int& rot) {
;     ...
;     for (int it = g0; it < items; it += NGW) {
;         const int kb = it / nblk, nb = it % nblk, k0 = 64 * kb, n0 = 32 * nb;
;         const int prow = n0 + (lane & 31); const bool ok = prow < Nvalid; const int col = ok ? colmap(mode, prow) : 0;
;         float wv_[32];
; #pragma unroll
;         for (int i = 0; i < 32; ++i) { const int kk = 2 * i + (lane >> 5); wv_[i] = ok ? W[(size_t)(k0 + kk) * ldw + col] : 0.f; }
.LBB0_520:
	s_ashr_i32 s12, s0, 31
	s_lshr_b32 s12, s12, 27
	s_add_i32 s12, s0, s12
	s_ashr_i32 s17, s12, 5
	s_lshl_b32 s13, s17, 10
	v_subrev_u32_e32 v6, s13, v13
	v_cmp_gt_i32_e32 vcc, s3, v6
	s_lshl_b32 s12, s17, 6
	v_or_b32_e32 v8, s12, v4
	v_cndmask_b32_e32 v6, 0, v6, vcc
	v_ashrrev_i32_e32 v7, 31, v6
	v_lshl_add_u64 v[6:7], v[6:7], 2, s[10:11]
	v_mov_b32_e32 v14, 0
	v_mov_b32_e32 v9, 0
	s_and_saveexec_b64 s[14:15], vcc
	s_cbranch_execz .LBB0_522
	v_ashrrev_i32_e32 v9, 31, v8
	v_lshlrev_b64 v[16:17], 12, v[8:9]
	v_lshl_add_u64 v[16:17], v[6:7], 0, v[16:17]
	global_load_dword v9, v[16:17], off nt
.LBB0_522:
	s_or_b64 exec, exec, s[14:15]
	s_and_saveexec_b64 s[14:15], vcc
	s_cbranch_execz .LBB0_524
	v_or_b32_e32 v14, 2, v8
	v_ashrrev_i32_e32 v15, 31, v14
	v_lshlrev_b64 v[14:15], 12, v[14:15]
	v_lshl_add_u64 v[14:15], v[6:7], 0, v[14:15]
	global_load_dword v14, v[14:15], off nt
.LBB0_524:
	s_or_b64 exec, exec, s[14:15]
	v_mov_b32_e32 v15, 0
	v_mov_b32_e32 v16, 0
	s_and_saveexec_b64 s[14:15], vcc
	s_cbranch_execz .LBB0_526
	v_or_b32_e32 v16, 4, v8
	v_ashrrev_i32_e32 v17, 31, v16
	v_lshlrev_b64 v[16:17], 12, v[16:17]
	v_lshl_add_u64 v[16:17], v[6:7], 0, v[16:17]
	global_load_dword v16, v[16:17], off nt
.LBB0_526:
	s_or_b64 exec, exec, s[14:15]
	s_and_saveexec_b64 s[14:15], vcc
	s_cbranch_execz .LBB0_528
	v_or_b32_e32 v20, 6, v8
	v_ashrrev_i32_e32 v21, 31, v20
	v_lshlrev_b64 v[20:21], 12, v[20:21]
	v_lshl_add_u64 v[20:21], v[6:7], 0, v[20:21]
	global_load_dword v15, v[20:21], off nt
.LBB0_528:
	s_or_b64 exec, exec, s[14:15]
	v_mov_b32_e32 v17, 0
	v_mov_b32_e32 v20, 0
	s_and_saveexec_b64 s[14:15], vcc
	s_cbranch_execz .LBB0_530
	v_or_b32_e32 v20, 8, v8
	v_ashrrev_i32_e32 v21, 31, v20
	v_lshlrev_b64 v[20:21], 12, v[20:21]
	v_lshl_add_u64 v[20:21], v[6:7], 0, v[20:21]
	global_load_dword v20, v[20:21], off nt
.LBB0_530:
	s_or_b64 exec, exec, s[14:15]
	s_and_saveexec_b64 s[14:15], vcc
	s_cbranch_execz .LBB0_532
	v_or_b32_e32 v22, 10, v8
	v_ashrrev_i32_e32 v23, 31, v22
	v_lshlrev_b64 v[22:23], 12, v[22:23]
	v_lshl_add_u64 v[22:23], v[6:7], 0, v[22:23]
	global_load_dword v17, v[22:23], off nt
.LBB0_532:
	s_or_b64 exec, exec, s[14:15]
	v_mov_b32_e32 v21, 0
	v_mov_b32_e32 v22, 0
	s_and_saveexec_b64 s[14:15], vcc
	s_cbranch_execz .LBB0_534
	v_or_b32_e32 v22, 12, v8
	v_ashrrev_i32_e32 v23, 31, v22
	v_lshlrev_b64 v[22:23], 12, v[22:23]
	v_lshl_add_u64 v[22:23], v[6:7], 0, v[22:23]
	global_load_dword v22, v[22:23], off nt
.LBB0_534:
	s_or_b64 exec, exec, s[14:15]
	s_and_saveexec_b64 s[14:15], vcc
	s_cbranch_execz .LBB0_536
	v_or_b32_e32 v24, 14, v8
	v_ashrrev_i32_e32 v25, 31, v24
	v_lshlrev_b64 v[24:25], 12, v[24:25]
	v_lshl_add_u64 v[24:25], v[6:7], 0, v[24:25]
	global_load_dword v21, v[24:25], off nt
.LBB0_536:
	s_or_b64 exec, exec, s[14:15]
	v_mov_b32_e32 v23, 0
	v_mov_b32_e32 v24, 0
	s_and_saveexec_b64 s[14:15], vcc
	s_cbranch_execz .LBB0_538
	v_or_b32_e32 v24, 16, v8
	v_ashrrev_i32_e32 v25, 31, v24
	v_lshlrev_b64 v[24:25], 12, v[24:25]
	v_lshl_add_u64 v[24:25], v[6:7], 0, v[24:25]
	global_load_dword v24, v[24:25], off nt
.LBB0_538:
	s_or_b64 exec, exec, s[14:15]
	s_and_saveexec_b64 s[14:15], vcc
	s_cbranch_execz .LBB0_540
	v_or_b32_e32 v26, 18, v8
	v_ashrrev_i32_e32 v27, 31, v26
	v_lshlrev_b64 v[26:27], 12, v[26:27]
	v_lshl_add_u64 v[26:27], v[6:7], 0, v[26:27]
	global_load_dword v23, v[26:27], off nt
.LBB0_540:
	s_or_b64 exec, exec, s[14:15]
	v_mov_b32_e32 v25, 0
	v_mov_b32_e32 v26, 0
	s_and_saveexec_b64 s[14:15], vcc
	s_cbranch_execz .LBB0_542
	v_or_b32_e32 v26, 20, v8
	v_ashrrev_i32_e32 v27, 31, v26
	v_lshlrev_b64 v[26:27], 12, v[26:27]
	v_lshl_add_u64 v[26:27], v[6:7], 0, v[26:27]
	global_load_dword v26, v[26:27], off nt
.LBB0_542:
	s_or_b64 exec, exec, s[14:15]
	s_and_saveexec_b64 s[14:15], vcc
	s_cbranch_execz .LBB0_544
	v_or_b32_e32 v28, 22, v8
	v_ashrrev_i32_e32 v29, 31, v28
	v_lshlrev_b64 v[28:29], 12, v[28:29]
	v_lshl_add_u64 v[28:29], v[6:7], 0, v[28:29]
	global_load_dword v25, v[28:29], off nt
.LBB0_544:
	s_or_b64 exec, exec, s[14:15]
	v_mov_b32_e32 v27, 0
	v_mov_b32_e32 v28, 0
	s_and_saveexec_b64 s[14:15], vcc
	s_cbranch_execz .LBB0_546
	v_or_b32_e32 v28, 24, v8
	v_ashrrev_i32_e32 v29, 31, v28
	v_lshlrev_b64 v[28:29], 12, v[28:29]
	v_lshl_add_u64 v[28:29], v[6:7], 0, v[28:29]
	global_load_dword v28, v[28:29], off nt
.LBB0_546:
	s_or_b64 exec, exec, s[14:15]
	s_and_saveexec_b64 s[14:15], vcc
	s_cbranch_execz .LBB0_548
	v_or_b32_e32 v32, 26, v8
	v_ashrrev_i32_e32 v33, 31, v32
	v_lshlrev_b64 v[32:33], 12, v[32:33]
	v_lshl_add_u64 v[32:33], v[6:7], 0, v[32:33]
	global_load_dword v27, v[32:33], off nt
.LBB0_548:
	s_or_b64 exec, exec, s[14:15]
	v_mov_b32_e32 v29, 0
	v_mov_b32_e32 v31, 0
	s_and_saveexec_b64 s[14:15], vcc
	s_cbranch_execz .LBB0_550
	v_or_b32_e32 v32, 28, v8
	v_ashrrev_i32_e32 v33, 31, v32
	v_lshlrev_b64 v[32:33], 12, v[32:33]
	v_lshl_add_u64 v[32:33], v[6:7], 0, v[32:33]
	global_load_dword v31, v[32:33], off nt
.LBB0_550:
	s_or_b64 exec, exec, s[14:15]
	s_and_saveexec_b64 s[14:15], vcc
	s_cbranch_execz .LBB0_552
	v_or_b32_e32 v32, 30, v8
	v_ashrrev_i32_e32 v33, 31, v32
	v_lshlrev_b64 v[32:33], 12, v[32:33]
	v_lshl_add_u64 v[32:33], v[6:7], 0, v[32:33]
	global_load_dword v29, v[32:33], off nt
; __device__ __forceinline__ void conv_weight(const float* W, int ldw, int K, int Nphys, int Nvalid, int mode, const float* g, bf16_t* WT, LAS float* scr, int gw, int NGW, int lane, int& rot) {
;     ...
;         const int prow = n0 + (lane & 31); const bool ok = prow < Nvalid; const int col = ok ? colmap(mode, prow) : 0;
;         float wv_[32];
; #pragma unroll
;         for (int i = 0; i < 32; ++i) { const int kk = 2 * i + (lane >> 5); wv_[i] = ok ? W[(size_t)(k0 + kk) * ldw + col] : 0.f; }
.LBB0_552:
	s_or_b64 exec, exec, s[14:15]
	v_mov_b32_e32 v32, 0
	v_mov_b32_e32 v33, 0
	s_and_saveexec_b64 s[14:15], vcc
	s_cbranch_execz .LBB0_554
	v_or_b32_e32 v40, 32, v8
	v_ashrrev_i32_e32 v41, 31, v40
	v_lshlrev_b64 v[40:41], 12, v[40:41]
	v_lshl_add_u64 v[40:41], v[6:7], 0, v[40:41]
	global_load_dword v33, v[40:41], off nt
.LBB0_554:
	s_or_b64 exec, exec, s[14:15]
	s_and_saveexec_b64 s[14:15], vcc
	s_cbranch_execz .LBB0_556
	v_or_b32_e32 v40, 34, v8
	v_ashrrev_i32_e32 v41, 31, v40
	v_lshlrev_b64 v[40:41], 12, v[40:41]
	v_lshl_add_u64 v[40:41], v[6:7], 0, v[40:41]
	global_load_dword v32, v[40:41], off nt
.LBB0_556:
	s_or_b64 exec, exec, s[14:15]
	v_mov_b32_e32 v39, 0
	v_mov_b32_e32 v40, 0
	s_and_saveexec_b64 s[14:15], vcc
	s_cbranch_execz .LBB0_558
	v_or_b32_e32 v40, 36, v8
	v_ashrrev_i32_e32 v41, 31, v40
	v_lshlrev_b64 v[40:41], 12, v[40:41]
	v_lshl_add_u64 v[40:41], v[6:7], 0, v[40:41]
	global_load_dword v40, v[40:41], off nt
.LBB0_558:
	s_or_b64 exec, exec, s[14:15]
	s_and_saveexec_b64 s[14:15], vcc
	s_cbranch_execz .LBB0_560
	v_or_b32_e32 v42, 38, v8
	v_ashrrev_i32_e32 v43, 31, v42
	v_lshlrev_b64 v[42:43], 12, v[42:43]
	v_lshl_add_u64 v[42:43], v[6:7], 0, v[42:43]
	global_load_dword v39, v[42:43], off nt
.LBB0_560:
	s_or_b64 exec, exec, s[14:15]
	v_mov_b32_e32 v41, 0
	v_mov_b32_e32 v42, 0
	s_and_saveexec_b64 s[14:15], vcc
	s_cbranch_execz .LBB0_562
	v_or_b32_e32 v42, 40, v8
	v_ashrrev_i32_e32 v43, 31, v42
	v_lshlrev_b64 v[42:43], 12, v[42:43]
	v_lshl_add_u64 v[42:43], v[6:7], 0, v[42:43]
	global_load_dword v42, v[42:43], off nt
.LBB0_562:
	s_or_b64 exec, exec, s[14:15]
	s_and_saveexec_b64 s[14:15], vcc
	s_cbranch_execz .LBB0_564
	v_or_b32_e32 v44, 42, v8
	v_ashrrev_i32_e32 v45, 31, v44
	v_lshlrev_b64 v[44:45], 12, v[44:45]
	v_lshl_add_u64 v[44:45], v[6:7], 0, v[44:45]
	global_load_dword v41, v[44:45], off nt
.LBB0_564:
	s_or_b64 exec, exec, s[14:15]
	v_mov_b32_e32 v43, 0
	v_mov_b32_e32 v44, 0
	s_and_saveexec_b64 s[14:15], vcc
	s_cbranch_execz .LBB0_566
	v_or_b32_e32 v44, 44, v8
	v_ashrrev_i32_e32 v45, 31, v44
	v_lshlrev_b64 v[44:45], 12, v[44:45]
	v_lshl_add_u64 v[44:45], v[6:7], 0, v[44:45]
	global_load_dword v44, v[44:45], off nt
.LBB0_566:
	s_or_b64 exec, exec, s[14:15]
	s_and_saveexec_b64 s[14:15], vcc
	s_cbranch_execz .LBB0_568
	v_or_b32_e32 v46, 46, v8
	v_ashrrev_i32_e32 v47, 31, v46
	v_lshlrev_b64 v[46:47], 12, v[46:47]
	v_lshl_add_u64 v[46:47], v[6:7], 0, v[46:47]
	global_load_dword v43, v[46:47], off nt
.LBB0_568:
	s_or_b64 exec, exec, s[14:15]
	v_mov_b32_e32 v45, 0
	v_mov_b32_e32 v46, 0
	s_and_saveexec_b64 s[14:15], vcc
	s_cbranch_execz .LBB0_570
	v_or_b32_e32 v46, 48, v8
	v_ashrrev_i32_e32 v47, 31, v46
	v_lshlrev_b64 v[46:47], 12, v[46:47]
	v_lshl_add_u64 v[46:47], v[6:7], 0, v[46:47]
	global_load_dword v46, v[46:47], off nt
.LBB0_570:
	s_or_b64 exec, exec, s[14:15]
	s_and_saveexec_b64 s[14:15], vcc
	s_cbranch_execz .LBB0_572
	v_or_b32_e32 v48, 50, v8
	v_ashrrev_i32_e32 v49, 31, v48
	v_lshlrev_b64 v[48:49], 12, v[48:49]
	v_lshl_add_u64 v[48:49], v[6:7], 0, v[48:49]
	global_load_dword v45, v[48:49], off nt
.LBB0_572:
	s_or_b64 exec, exec, s[14:15]
	v_mov_b32_e32 v47, 0
	v_mov_b32_e32 v48, 0
	s_and_saveexec_b64 s[14:15], vcc
	s_cbranch_execz .LBB0_574
	v_or_b32_e32 v48, 52, v8
	v_ashrrev_i32_e32 v49, 31, v48
	v_lshlrev_b64 v[48:49], 12, v[48:49]
	v_lshl_add_u64 v[48:49], v[6:7], 0, v[48:49]
	global_load_dword v48, v[48:49], off nt
.LBB0_574:
	s_or_b64 exec, exec, s[14:15]
	s_and_saveexec_b64 s[14:15], vcc
	s_cbranch_execz .LBB0_576
	v_or_b32_e32 v50, 54, v8
	v_ashrrev_i32_e32 v51, 31, v50
	v_lshlrev_b64 v[50:51], 12, v[50:51]
	v_lshl_add_u64 v[50:51], v[6:7], 0, v[50:51]
	global_load_dword v47, v[50:51], off nt
.LBB0_576:
	s_or_b64 exec, exec, s[14:15]
	v_mov_b32_e32 v49, 0
	v_mov_b32_e32 v50, 0
	s_and_saveexec_b64 s[14:15], vcc
	s_cbranch_execz .LBB0_578
	v_or_b32_e32 v50, 56, v8
	v_ashrrev_i32_e32 v51, 31, v50
	v_lshlrev_b64 v[50:51], 12, v[50:51]
	v_lshl_add_u64 v[50:51], v[6:7], 0, v[50:51]
	global_load_dword v50, v[50:51], off nt
.LBB0_578:
	s_or_b64 exec, exec, s[14:15]
	s_and_saveexec_b64 s[14:15], vcc
	s_cbranch_execz .LBB0_580
	v_or_b32_e32 v52, 58, v8
	v_ashrrev_i32_e32 v53, 31, v52
	v_lshlrev_b64 v[52:53], 12, v[52:53]
	v_lshl_add_u64 v[52:53], v[6:7], 0, v[52:53]
	global_load_dword v49, v[52:53], off nt
.LBB0_580:
	s_or_b64 exec, exec, s[14:15]
	v_mov_b32_e32 v51, 0
	v_mov_b32_e32 v52, 0
	s_and_saveexec_b64 s[14:15], vcc
	s_cbranch_execz .LBB0_582
	v_or_b32_e32 v52, 60, v8
	v_ashrrev_i32_e32 v53, 31, v52
	v_lshlrev_b64 v[52:53], 12, v[52:53]
	v_lshl_add_u64 v[52:53], v[6:7], 0, v[52:53]
	global_load_dword v52, v[52:53], off nt
.LBB0_582:
	s_or_b64 exec, exec, s[14:15]
	s_and_saveexec_b64 s[14:15], vcc
	s_cbranch_execz .LBB0_519
	v_or_b32_e32 v54, 62, v8
	v_ashrrev_i32_e32 v55, 31, v54
	v_lshlrev_b64 v[54:55], 12, v[54:55]
	v_lshl_add_u64 v[6:7], v[6:7], 0, v[54:55]
	global_load_dword v51, v[6:7], off nt
	s_branch .LBB0_519

; __global__ void __launch_bounds__(512, 2) fwd_kernel(Args args) {
;     ...
;             for (int m = gw; m < S; m += NGW) {
;                 const f32x4* xr = (const f32x4*)(x + (size_t)m * D) + lane; f32x4 v[4]; float s = 0.f;
; #pragma unroll
;                 for (int j = 0; j < 4; ++j) { v[j] = xr[64 * j]; s += (v[j][0] * v[j][0] + v[j][1] * v[j][1]) + (v[j][2] * v[j][2] + v[j][3] * v[j][3]); }
;                 s = wave_sum(s); if (lane == 0) ssq[m] = s;
.LBB0_587:
	global_load_dwordx4 v[14:17], v[22:23], off offset:-3072 nt
	global_load_dwordx4 v[10:13], v[22:23], off offset:-2048 nt
	global_load_dwordx4 v[6:9], v[22:23], off offset:-1024 nt
	global_load_dwordx4 v[2:5], v[22:23], off nt
	s_waitcnt vmcnt(3)
	v_mul_f32_e32 v19, v15, v15
	s_waitcnt lgkmcnt(0)
	v_mul_f32_e32 v34, v17, v17
	s_waitcnt vmcnt(2)
	v_mul_f32_e32 v35, v11, v11
	v_mul_f32_e32 v36, v13, v13
	s_waitcnt vmcnt(1)
	v_mul_f32_e32 v37, v7, v7
	v_mul_f32_e32 v38, v9, v9
	v_fmac_f32_e32 v19, v14, v14
	v_fmac_f32_e32 v34, v16, v16
	v_fmac_f32_e32 v35, v10, v10
	v_fmac_f32_e32 v36, v12, v12
	s_waitcnt vmcnt(0)
	v_mul_f32_e32 v39, v3, v3
	v_mul_f32_e32 v40, v5, v5
	v_fmac_f32_e32 v37, v6, v6
	v_fmac_f32_e32 v38, v8, v8
	v_add_f32_e32 v19, v19, v34
	v_add_f32_e32 v34, v35, v36
	v_fmac_f32_e32 v39, v2, v2
	v_fmac_f32_e32 v40, v4, v4
	v_add_f32_e32 v35, v37, v38
	v_add_f32_e32 v19, v19, v34
	v_add_f32_e32 v19, v19, v35
	v_add_f32_e32 v34, v39, v40
	v_add_f32_e32 v19, v19, v34
	ds_bpermute_b32 v34, v26, v19
	s_waitcnt lgkmcnt(0)
	v_add_f32_e32 v19, v19, v34
	ds_bpermute_b32 v34, v27, v19
	s_waitcnt lgkmcnt(0)
	v_add_f32_e32 v19, v19, v34
	ds_bpermute_b32 v34, v28, v19
	s_waitcnt lgkmcnt(0)
	v_add_f32_e32 v19, v19, v34
	ds_bpermute_b32 v34, v29, v19
	s_waitcnt lgkmcnt(0)
	v_add_f32_e32 v19, v19, v34
	ds_bpermute_b32 v34, v31, v19
	s_waitcnt lgkmcnt(0)
	v_add_f32_e32 v19, v19, v34
	ds_bpermute_b32 v34, v33, v19
	s_and_saveexec_b64 s[24:25], vcc
	s_cbranch_execz .LBB0_586
	s_waitcnt lgkmcnt(0)
	v_add_f32_e32 v19, v19, v34
	global_store_dword v21, v19, s[4:5]
	s_branch .LBB0_586
